# GEMM unit setup: removed the duplicated accumulator zero-init (second copy of 128 v_mov) in all 16 GEMM instances
# speedup vs baseline: 1.0568x; 1.0123x over previous
.LBB0_40:
	s_ashr_i32 s61, s60, 31
	s_lshl_b64 s[20:21], s[60:61], 21
	s_add_u32 s64, s24, s20
	s_addc_u32 s65, s25, s21
	s_ashr_i32 s63, s62, 31
	s_lshl_b64 s[20:21], s[62:63], 21
	v_readlane_b32 s42, v254, 54
	s_add_u32 s66, s42, s20
	v_readlane_b32 s20, v254, 62
	v_mov_b32_e32 v127, 0
	s_addc_u32 s67, s20, s21
	s_andn2_b64 vcc, exec, s[56:57]
	v_mov_b32_e32 v126, v127
	v_mov_b32_e32 v125, v127
	v_mov_b32_e32 v124, v127
	v_mov_b32_e32 v123, v127
	v_mov_b32_e32 v122, v127
	v_mov_b32_e32 v121, v127
	v_mov_b32_e32 v120, v127
	v_mov_b32_e32 v111, v127
	v_mov_b32_e32 v110, v127
	v_mov_b32_e32 v109, v127
	v_mov_b32_e32 v108, v127
	v_mov_b32_e32 v107, v127
	v_mov_b32_e32 v106, v127
	v_mov_b32_e32 v105, v127
	v_mov_b32_e32 v104, v127
	v_mov_b32_e32 v95, v127
	v_mov_b32_e32 v94, v127
	v_mov_b32_e32 v93, v127
	v_mov_b32_e32 v92, v127
	v_mov_b32_e32 v91, v127
	v_mov_b32_e32 v90, v127
	v_mov_b32_e32 v89, v127
	v_mov_b32_e32 v88, v127
	v_mov_b32_e32 v79, v127
	v_mov_b32_e32 v78, v127
	v_mov_b32_e32 v77, v127
	v_mov_b32_e32 v76, v127
	v_mov_b32_e32 v75, v127
	v_mov_b32_e32 v74, v127
	v_mov_b32_e32 v73, v127
	v_mov_b32_e32 v72, v127
	v_mov_b32_e32 v119, v127
	v_mov_b32_e32 v118, v127
	v_mov_b32_e32 v117, v127
	v_mov_b32_e32 v116, v127
	v_mov_b32_e32 v115, v127
	v_mov_b32_e32 v114, v127
	v_mov_b32_e32 v113, v127
	v_mov_b32_e32 v112, v127
	v_mov_b32_e32 v103, v127
	v_mov_b32_e32 v102, v127
	v_mov_b32_e32 v101, v127
	v_mov_b32_e32 v100, v127
	v_mov_b32_e32 v99, v127
	v_mov_b32_e32 v98, v127
	v_mov_b32_e32 v97, v127
	v_mov_b32_e32 v96, v127
	v_mov_b32_e32 v87, v127
	v_mov_b32_e32 v86, v127
	v_mov_b32_e32 v85, v127
	v_mov_b32_e32 v84, v127
	v_mov_b32_e32 v83, v127
	v_mov_b32_e32 v82, v127
	v_mov_b32_e32 v81, v127
	v_mov_b32_e32 v80, v127
	v_mov_b32_e32 v71, v127
	v_mov_b32_e32 v70, v127
	v_mov_b32_e32 v69, v127
	v_mov_b32_e32 v68, v127
	v_mov_b32_e32 v67, v127
	v_mov_b32_e32 v66, v127
	v_mov_b32_e32 v65, v127
	v_mov_b32_e32 v64, v127
	v_mov_b32_e32 v63, v127
	v_mov_b32_e32 v62, v127
	v_mov_b32_e32 v61, v127
	v_mov_b32_e32 v60, v127
	v_mov_b32_e32 v59, v127
	v_mov_b32_e32 v58, v127
	v_mov_b32_e32 v57, v127
	v_mov_b32_e32 v56, v127
	v_mov_b32_e32 v47, v127
	v_mov_b32_e32 v46, v127
	v_mov_b32_e32 v45, v127
	v_mov_b32_e32 v44, v127
	v_mov_b32_e32 v43, v127
	v_mov_b32_e32 v42, v127
	v_mov_b32_e32 v41, v127
	v_mov_b32_e32 v40, v127
	v_mov_b32_e32 v31, v127
	v_mov_b32_e32 v30, v127
	v_mov_b32_e32 v29, v127
	v_mov_b32_e32 v28, v127
	v_mov_b32_e32 v27, v127
	v_mov_b32_e32 v26, v127
	v_mov_b32_e32 v25, v127
	v_mov_b32_e32 v24, v127
	v_mov_b32_e32 v15, v127
	v_mov_b32_e32 v14, v127
	v_mov_b32_e32 v13, v127
	v_mov_b32_e32 v12, v127
	v_mov_b32_e32 v11, v127
	v_mov_b32_e32 v10, v127
	v_mov_b32_e32 v9, v127
	v_mov_b32_e32 v8, v127
	v_mov_b32_e32 v55, v127
	v_mov_b32_e32 v54, v127
	v_mov_b32_e32 v53, v127
	v_mov_b32_e32 v52, v127
	v_mov_b32_e32 v51, v127
	v_mov_b32_e32 v50, v127
	v_mov_b32_e32 v49, v127
	v_mov_b32_e32 v48, v127
	v_mov_b32_e32 v39, v127
	v_mov_b32_e32 v38, v127
	v_mov_b32_e32 v37, v127
	v_mov_b32_e32 v36, v127
	v_mov_b32_e32 v35, v127
	v_mov_b32_e32 v34, v127
	v_mov_b32_e32 v33, v127
	v_mov_b32_e32 v32, v127
	v_mov_b32_e32 v23, v127
	v_mov_b32_e32 v22, v127
	v_mov_b32_e32 v21, v127
	v_mov_b32_e32 v20, v127
	v_mov_b32_e32 v19, v127
	v_mov_b32_e32 v18, v127
	v_mov_b32_e32 v17, v127
	v_mov_b32_e32 v16, v127
	v_mov_b32_e32 v7, v127
	v_mov_b32_e32 v6, v127
	v_mov_b32_e32 v5, v127
	v_mov_b32_e32 v4, v127
	s_waitcnt lgkmcnt(0)
	v_mov_b32_e32 v3, v127
	v_mov_b32_e32 v2, v127
	v_mov_b32_e32 v1, v127
	v_mov_b32_e32 v0, v127
	s_cbranch_vccnz .LBB0_43
	s_and_b64 s[20:21], s[38:39], exec
	s_cselect_b32 s42, s65, s1
	s_cselect_b32 s43, s64, s0
	s_cselect_b32 s44, s67, s3
	s_cselect_b32 s45, s66, s2
	s_add_u32 s0, s0, 0x100080
	s_addc_u32 s1, s1, 0
	s_add_u32 s46, s2, 0x100
	s_addc_u32 s47, s3, 0
	s_mov_b32 s2, 0

.LBB0_88:
	s_ashr_i32 s61, s60, 31
	s_lshl_b64 s[20:21], s[60:61], 21
	s_add_u32 s64, s24, s20
	s_addc_u32 s65, s25, s21
	s_ashr_i32 s63, s62, 31
	s_lshl_b64 s[20:21], s[62:63], 21
	v_readlane_b32 s22, v254, 54
	s_add_u32 s66, s22, s20
	v_readlane_b32 s20, v254, 62
	v_mov_b32_e32 v127, 0
	s_addc_u32 s67, s20, s21
	s_andn2_b64 vcc, exec, s[42:43]
	v_mov_b32_e32 v126, v127
	v_mov_b32_e32 v125, v127
	v_mov_b32_e32 v124, v127
	v_mov_b32_e32 v123, v127
	v_mov_b32_e32 v122, v127
	v_mov_b32_e32 v121, v127
	v_mov_b32_e32 v120, v127
	v_mov_b32_e32 v111, v127
	v_mov_b32_e32 v110, v127
	v_mov_b32_e32 v109, v127
	v_mov_b32_e32 v108, v127
	v_mov_b32_e32 v107, v127
	v_mov_b32_e32 v106, v127
	v_mov_b32_e32 v105, v127
	v_mov_b32_e32 v104, v127
	v_mov_b32_e32 v95, v127
	v_mov_b32_e32 v94, v127
	v_mov_b32_e32 v93, v127
	v_mov_b32_e32 v92, v127
	v_mov_b32_e32 v91, v127
	v_mov_b32_e32 v90, v127
	v_mov_b32_e32 v89, v127
	v_mov_b32_e32 v88, v127
	v_mov_b32_e32 v79, v127
	v_mov_b32_e32 v78, v127
	v_mov_b32_e32 v77, v127
	v_mov_b32_e32 v76, v127
	v_mov_b32_e32 v75, v127
	v_mov_b32_e32 v74, v127
	v_mov_b32_e32 v73, v127
	v_mov_b32_e32 v72, v127
	v_mov_b32_e32 v119, v127
	v_mov_b32_e32 v118, v127
	v_mov_b32_e32 v117, v127
	v_mov_b32_e32 v116, v127
	v_mov_b32_e32 v115, v127
	v_mov_b32_e32 v114, v127
	v_mov_b32_e32 v113, v127
	v_mov_b32_e32 v112, v127
	v_mov_b32_e32 v103, v127
	v_mov_b32_e32 v102, v127
	v_mov_b32_e32 v101, v127
	v_mov_b32_e32 v100, v127
	v_mov_b32_e32 v99, v127
	v_mov_b32_e32 v98, v127
	v_mov_b32_e32 v97, v127
	v_mov_b32_e32 v96, v127
	v_mov_b32_e32 v87, v127
	v_mov_b32_e32 v86, v127
	v_mov_b32_e32 v85, v127
	v_mov_b32_e32 v84, v127
	v_mov_b32_e32 v83, v127
	v_mov_b32_e32 v82, v127
	v_mov_b32_e32 v81, v127
	v_mov_b32_e32 v80, v127
	v_mov_b32_e32 v71, v127
	v_mov_b32_e32 v70, v127
	v_mov_b32_e32 v69, v127
	v_mov_b32_e32 v68, v127
	v_mov_b32_e32 v67, v127
	v_mov_b32_e32 v66, v127
	v_mov_b32_e32 v65, v127
	v_mov_b32_e32 v64, v127
	v_mov_b32_e32 v63, v127
	v_mov_b32_e32 v62, v127
	v_mov_b32_e32 v61, v127
	v_mov_b32_e32 v60, v127
	v_mov_b32_e32 v59, v127
	v_mov_b32_e32 v58, v127
	v_mov_b32_e32 v57, v127
	v_mov_b32_e32 v56, v127
	v_mov_b32_e32 v47, v127
	v_mov_b32_e32 v46, v127
	v_mov_b32_e32 v45, v127
	v_mov_b32_e32 v44, v127
	v_mov_b32_e32 v43, v127
	v_mov_b32_e32 v42, v127
	v_mov_b32_e32 v41, v127
	v_mov_b32_e32 v40, v127
	v_mov_b32_e32 v31, v127
	v_mov_b32_e32 v30, v127
	v_mov_b32_e32 v29, v127
	v_mov_b32_e32 v28, v127
	v_mov_b32_e32 v27, v127
	v_mov_b32_e32 v26, v127
	v_mov_b32_e32 v25, v127
	v_mov_b32_e32 v24, v127
	v_mov_b32_e32 v15, v127
	v_mov_b32_e32 v14, v127
	v_mov_b32_e32 v13, v127
	v_mov_b32_e32 v12, v127
	v_mov_b32_e32 v11, v127
	v_mov_b32_e32 v10, v127
	v_mov_b32_e32 v9, v127
	v_mov_b32_e32 v8, v127
	v_mov_b32_e32 v55, v127
	v_mov_b32_e32 v54, v127
	v_mov_b32_e32 v53, v127
	v_mov_b32_e32 v52, v127
	v_mov_b32_e32 v51, v127
	v_mov_b32_e32 v50, v127
	v_mov_b32_e32 v49, v127
	v_mov_b32_e32 v48, v127
	v_mov_b32_e32 v39, v127
	v_mov_b32_e32 v38, v127
	v_mov_b32_e32 v37, v127
	v_mov_b32_e32 v36, v127
	v_mov_b32_e32 v35, v127
	v_mov_b32_e32 v34, v127
	v_mov_b32_e32 v33, v127
	v_mov_b32_e32 v32, v127
	v_mov_b32_e32 v23, v127
	v_mov_b32_e32 v22, v127
	v_mov_b32_e32 v21, v127
	v_mov_b32_e32 v20, v127
	v_mov_b32_e32 v19, v127
	v_mov_b32_e32 v18, v127
	v_mov_b32_e32 v17, v127
	v_mov_b32_e32 v16, v127
	v_mov_b32_e32 v7, v127
	v_mov_b32_e32 v6, v127
	v_mov_b32_e32 v5, v127
	v_mov_b32_e32 v4, v127
	s_waitcnt lgkmcnt(0)
	v_mov_b32_e32 v3, v127
	v_mov_b32_e32 v2, v127
	v_mov_b32_e32 v1, v127
	v_mov_b32_e32 v0, v127
	s_cbranch_vccnz .LBB0_92
	s_and_b64 s[20:21], s[38:39], exec
	s_mov_b64 s[68:69], s[42:43]
	s_cselect_b32 s22, s65, s1
	s_cselect_b32 s23, s64, s0
	s_cselect_b32 s34, s67, s3
	s_cselect_b32 s42, s66, s2
	s_add_u32 s0, s0, 0x100080
	s_addc_u32 s1, s1, 0
	s_add_u32 s43, s2, 0x100
	s_addc_u32 s44, s3, 0
	s_mov_b32 s2, 0

.LBB0_136:
	s_ashr_i32 s65, s64, 31
	s_lshl_b64 s[26:27], s[64:65], 19
	v_readlane_b32 s40, v254, 43
	v_readlane_b32 s41, v254, 44
	s_add_u32 s68, s40, s26
	s_addc_u32 s69, s41, s27
	s_ashr_i32 s67, s66, 31
	s_lshl_b64 s[26:27], s[66:67], 19
	s_add_u32 s70, s34, s26
	v_mov_b32_e32 v155, 0
	s_addc_u32 s71, s72, s27
	s_andn2_b64 vcc, exec, s[60:61]
	v_mov_b32_e32 v154, v155
	v_mov_b32_e32 v153, v155
	v_mov_b32_e32 v152, v155
	v_mov_b32_e32 v159, v155
	v_mov_b32_e32 v158, v155
	v_mov_b32_e32 v157, v155
	v_mov_b32_e32 v156, v155
	v_mov_b32_e32 v139, v155
	v_mov_b32_e32 v138, v155
	v_mov_b32_e32 v137, v155
	v_mov_b32_e32 v136, v155
	v_mov_b32_e32 v143, v155
	v_mov_b32_e32 v142, v155
	v_mov_b32_e32 v141, v155
	v_mov_b32_e32 v140, v155
	v_mov_b32_e32 v123, v155
	v_mov_b32_e32 v122, v155
	v_mov_b32_e32 v121, v155
	v_mov_b32_e32 v120, v155
	v_mov_b32_e32 v127, v155
	v_mov_b32_e32 v126, v155
	v_mov_b32_e32 v125, v155
	v_mov_b32_e32 v124, v155
	v_mov_b32_e32 v107, v155
	v_mov_b32_e32 v106, v155
	v_mov_b32_e32 v105, v155
	v_mov_b32_e32 v104, v155
	v_mov_b32_e32 v111, v155
	v_mov_b32_e32 v110, v155
	v_mov_b32_e32 v109, v155
	v_mov_b32_e32 v108, v155
	v_mov_b32_e32 v147, v155
	v_mov_b32_e32 v146, v155
	v_mov_b32_e32 v145, v155
	v_mov_b32_e32 v144, v155
	v_mov_b32_e32 v151, v155
	v_mov_b32_e32 v150, v155
	v_mov_b32_e32 v149, v155
	v_mov_b32_e32 v148, v155
	v_mov_b32_e32 v131, v155
	v_mov_b32_e32 v130, v155
	v_mov_b32_e32 v129, v155
	v_mov_b32_e32 v128, v155
	v_mov_b32_e32 v135, v155
	v_mov_b32_e32 v134, v155
	v_mov_b32_e32 v133, v155
	v_mov_b32_e32 v132, v155
	v_mov_b32_e32 v115, v155
	v_mov_b32_e32 v114, v155
	v_mov_b32_e32 v113, v155
	v_mov_b32_e32 v112, v155
	v_mov_b32_e32 v119, v155
	v_mov_b32_e32 v118, v155
	v_mov_b32_e32 v117, v155
	v_mov_b32_e32 v116, v155
	v_mov_b32_e32 v83, v155
	v_mov_b32_e32 v82, v155
	v_mov_b32_e32 v81, v155
	v_mov_b32_e32 v80, v155
	v_mov_b32_e32 v87, v155
	v_mov_b32_e32 v86, v155
	v_mov_b32_e32 v85, v155
	v_mov_b32_e32 v84, v155
	v_mov_b32_e32 v59, v155
	v_mov_b32_e32 v58, v155
	v_mov_b32_e32 v57, v155
	v_mov_b32_e32 v56, v155
	v_mov_b32_e32 v63, v155
	v_mov_b32_e32 v62, v155
	v_mov_b32_e32 v61, v155
	v_mov_b32_e32 v60, v155
	v_mov_b32_e32 v43, v155
	v_mov_b32_e32 v42, v155
	v_mov_b32_e32 v41, v155
	v_mov_b32_e32 v40, v155
	v_mov_b32_e32 v47, v155
	v_mov_b32_e32 v46, v155
	v_mov_b32_e32 v45, v155
	v_mov_b32_e32 v44, v155
	v_mov_b32_e32 v27, v155
	v_mov_b32_e32 v26, v155
	v_mov_b32_e32 v25, v155
	v_mov_b32_e32 v24, v155
	v_mov_b32_e32 v31, v155
	v_mov_b32_e32 v30, v155
	v_mov_b32_e32 v29, v155
	v_mov_b32_e32 v28, v155
	v_mov_b32_e32 v11, v155
	v_mov_b32_e32 v10, v155
	v_mov_b32_e32 v9, v155
	v_mov_b32_e32 v8, v155
	v_mov_b32_e32 v15, v155
	v_mov_b32_e32 v14, v155
	v_mov_b32_e32 v13, v155
	v_mov_b32_e32 v12, v155
	v_mov_b32_e32 v51, v155
	v_mov_b32_e32 v50, v155
	v_mov_b32_e32 v49, v155
	v_mov_b32_e32 v48, v155
	v_mov_b32_e32 v55, v155
	v_mov_b32_e32 v54, v155
	v_mov_b32_e32 v53, v155
	v_mov_b32_e32 v52, v155
	v_mov_b32_e32 v35, v155
	v_mov_b32_e32 v34, v155
	v_mov_b32_e32 v33, v155
	v_mov_b32_e32 v32, v155
	v_mov_b32_e32 v39, v155
	v_mov_b32_e32 v38, v155
	v_mov_b32_e32 v37, v155
	v_mov_b32_e32 v36, v155
	v_mov_b32_e32 v19, v155
	v_mov_b32_e32 v18, v155
	v_mov_b32_e32 v17, v155
	v_mov_b32_e32 v16, v155
	v_mov_b32_e32 v23, v155
	v_mov_b32_e32 v22, v155
	v_mov_b32_e32 v21, v155
	v_mov_b32_e32 v20, v155
	v_mov_b32_e32 v3, v155
	v_mov_b32_e32 v2, v155
	v_mov_b32_e32 v1, v155
	v_mov_b32_e32 v0, v155
	v_mov_b32_e32 v7, v155
	v_mov_b32_e32 v6, v155
	v_mov_b32_e32 v5, v155
	v_mov_b32_e32 v4, v155
	s_cbranch_vccnz .LBB0_139
	s_and_b64 s[26:27], s[38:39], exec
	s_cselect_b32 s1, s69, s21
	s_cselect_b32 s40, s68, s20
	s_cselect_b32 s41, s71, s23
	s_cselect_b32 s44, s70, s22
	s_add_u32 s20, s20, 0x40080
	s_addc_u32 s21, s21, 0
	s_add_u32 s45, s22, 0x100
	s_addc_u32 s53, s23, 0
	s_mov_b32 s22, 0

.LBB0_197:
	s_ashr_i32 s61, s60, 31
	s_lshl_b64 s[20:21], s[60:61], 19
	v_readlane_b32 s41, v254, 57
	s_add_u32 s64, s41, s20
	v_readlane_b32 s20, v254, 59
	s_addc_u32 s65, s20, s21
	s_ashr_i32 s63, s62, 31
	s_lshl_b64 s[20:21], s[62:63], 19
	s_add_u32 s66, s22, s20
	v_mov_b32_e32 v127, 0
	s_addc_u32 s67, s23, s21
	s_andn2_b64 vcc, exec, s[56:57]
	v_mov_b32_e32 v126, v127
	v_mov_b32_e32 v125, v127
	v_mov_b32_e32 v124, v127
	v_mov_b32_e32 v123, v127
	v_mov_b32_e32 v122, v127
	v_mov_b32_e32 v121, v127
	v_mov_b32_e32 v120, v127
	v_mov_b32_e32 v111, v127
	v_mov_b32_e32 v110, v127
	v_mov_b32_e32 v109, v127
	v_mov_b32_e32 v108, v127
	v_mov_b32_e32 v107, v127
	v_mov_b32_e32 v106, v127
	v_mov_b32_e32 v105, v127
	v_mov_b32_e32 v104, v127
	v_mov_b32_e32 v95, v127
	v_mov_b32_e32 v94, v127
	v_mov_b32_e32 v93, v127
	v_mov_b32_e32 v92, v127
	v_mov_b32_e32 v91, v127
	v_mov_b32_e32 v90, v127
	v_mov_b32_e32 v89, v127
	v_mov_b32_e32 v88, v127
	v_mov_b32_e32 v79, v127
	v_mov_b32_e32 v78, v127
	v_mov_b32_e32 v77, v127
	v_mov_b32_e32 v76, v127
	v_mov_b32_e32 v75, v127
	v_mov_b32_e32 v74, v127
	v_mov_b32_e32 v73, v127
	v_mov_b32_e32 v72, v127
	v_mov_b32_e32 v119, v127
	v_mov_b32_e32 v118, v127
	v_mov_b32_e32 v117, v127
	v_mov_b32_e32 v116, v127
	v_mov_b32_e32 v115, v127
	v_mov_b32_e32 v114, v127
	v_mov_b32_e32 v113, v127
	v_mov_b32_e32 v112, v127
	v_mov_b32_e32 v103, v127
	v_mov_b32_e32 v102, v127
	v_mov_b32_e32 v101, v127
	v_mov_b32_e32 v100, v127
	v_mov_b32_e32 v99, v127
	v_mov_b32_e32 v98, v127
	v_mov_b32_e32 v97, v127
	v_mov_b32_e32 v96, v127
	v_mov_b32_e32 v87, v127
	v_mov_b32_e32 v86, v127
	v_mov_b32_e32 v85, v127
	v_mov_b32_e32 v84, v127
	v_mov_b32_e32 v83, v127
	v_mov_b32_e32 v82, v127
	v_mov_b32_e32 v81, v127
	v_mov_b32_e32 v80, v127
	v_mov_b32_e32 v71, v127
	v_mov_b32_e32 v70, v127
	v_mov_b32_e32 v69, v127
	v_mov_b32_e32 v68, v127
	v_mov_b32_e32 v67, v127
	v_mov_b32_e32 v66, v127
	v_mov_b32_e32 v65, v127
	v_mov_b32_e32 v64, v127
	v_mov_b32_e32 v63, v127
	v_mov_b32_e32 v62, v127
	v_mov_b32_e32 v61, v127
	v_mov_b32_e32 v60, v127
	v_mov_b32_e32 v59, v127
	v_mov_b32_e32 v58, v127
	v_mov_b32_e32 v57, v127
	v_mov_b32_e32 v56, v127
	v_mov_b32_e32 v47, v127
	v_mov_b32_e32 v46, v127
	v_mov_b32_e32 v45, v127
	v_mov_b32_e32 v44, v127
	v_mov_b32_e32 v43, v127
	v_mov_b32_e32 v42, v127
	v_mov_b32_e32 v41, v127
	v_mov_b32_e32 v40, v127
	v_mov_b32_e32 v31, v127
	v_mov_b32_e32 v30, v127
	v_mov_b32_e32 v29, v127
	v_mov_b32_e32 v28, v127
	v_mov_b32_e32 v27, v127
	v_mov_b32_e32 v26, v127
	v_mov_b32_e32 v25, v127
	v_mov_b32_e32 v24, v127
	v_mov_b32_e32 v15, v127
	v_mov_b32_e32 v14, v127
	v_mov_b32_e32 v13, v127
	v_mov_b32_e32 v12, v127
	v_mov_b32_e32 v11, v127
	v_mov_b32_e32 v10, v127
	v_mov_b32_e32 v9, v127
	v_mov_b32_e32 v8, v127
	v_mov_b32_e32 v55, v127
	v_mov_b32_e32 v54, v127
	v_mov_b32_e32 v53, v127
	v_mov_b32_e32 v52, v127
	v_mov_b32_e32 v51, v127
	v_mov_b32_e32 v50, v127
	v_mov_b32_e32 v49, v127
	v_mov_b32_e32 v48, v127
	v_mov_b32_e32 v39, v127
	v_mov_b32_e32 v38, v127
	v_mov_b32_e32 v37, v127
	v_mov_b32_e32 v36, v127
	v_mov_b32_e32 v35, v127
	v_mov_b32_e32 v34, v127
	v_mov_b32_e32 v33, v127
	v_mov_b32_e32 v32, v127
	v_mov_b32_e32 v23, v127
	v_mov_b32_e32 v22, v127
	v_mov_b32_e32 v21, v127
	v_mov_b32_e32 v20, v127
	v_mov_b32_e32 v19, v127
	v_mov_b32_e32 v18, v127
	v_mov_b32_e32 v17, v127
	v_mov_b32_e32 v16, v127
	v_mov_b32_e32 v7, v127
	v_mov_b32_e32 v6, v127
	v_mov_b32_e32 v5, v127
	v_mov_b32_e32 v4, v127
	s_waitcnt lgkmcnt(0)
	v_mov_b32_e32 v3, v127
	v_mov_b32_e32 v2, v127
	v_mov_b32_e32 v1, v127
	v_mov_b32_e32 v0, v127
	s_cbranch_vccnz .LBB0_200
	s_and_b64 s[20:21], s[38:39], exec
	s_cselect_b32 s41, s65, s1
	s_cselect_b32 s42, s64, s0
	s_cselect_b32 s43, s67, s3
	s_cselect_b32 s44, s66, s2
	s_add_u32 s0, s0, 0x40080
	s_addc_u32 s1, s1, 0
	s_add_u32 s45, s2, 0x100
	s_addc_u32 s46, s3, 0
	s_mov_b32 s2, 0

.LBB0_248:
	v_mov_b32_e32 v127, 0
	s_andn2_b64 vcc, exec, s[20:21]
	v_mov_b32_e32 v126, 0
	v_mov_b32_e32 v125, 0
	v_mov_b32_e32 v124, 0
	v_mov_b32_e32 v123, 0
	v_mov_b32_e32 v122, 0
	v_mov_b32_e32 v121, 0
	v_mov_b32_e32 v120, 0
	v_mov_b32_e32 v111, 0
	v_mov_b32_e32 v110, 0
	v_mov_b32_e32 v109, 0
	v_mov_b32_e32 v108, 0
	v_mov_b32_e32 v107, 0
	v_mov_b32_e32 v106, 0
	v_mov_b32_e32 v105, 0
	v_mov_b32_e32 v104, 0
	v_mov_b32_e32 v95, 0
	v_mov_b32_e32 v94, 0
	v_mov_b32_e32 v93, 0
	v_mov_b32_e32 v92, 0
	v_mov_b32_e32 v91, 0
	v_mov_b32_e32 v90, 0
	v_mov_b32_e32 v89, 0
	v_mov_b32_e32 v88, 0
	v_mov_b32_e32 v79, 0
	v_mov_b32_e32 v78, 0
	v_mov_b32_e32 v77, 0
	v_mov_b32_e32 v76, 0
	v_mov_b32_e32 v75, 0
	v_mov_b32_e32 v74, 0
	v_mov_b32_e32 v73, 0
	v_mov_b32_e32 v72, 0
	v_mov_b32_e32 v119, 0
	v_mov_b32_e32 v118, 0
	v_mov_b32_e32 v117, 0
	v_mov_b32_e32 v116, 0
	v_mov_b32_e32 v115, 0
	v_mov_b32_e32 v114, 0
	v_mov_b32_e32 v113, 0
	v_mov_b32_e32 v112, 0
	v_mov_b32_e32 v103, 0
	v_mov_b32_e32 v102, 0
	v_mov_b32_e32 v101, 0
	v_mov_b32_e32 v100, 0
	v_mov_b32_e32 v99, 0
	v_mov_b32_e32 v98, 0
	v_mov_b32_e32 v97, 0
	v_mov_b32_e32 v96, 0
	v_mov_b32_e32 v87, 0
	v_mov_b32_e32 v86, 0
	v_mov_b32_e32 v85, 0
	v_mov_b32_e32 v84, 0
	v_mov_b32_e32 v83, 0
	v_mov_b32_e32 v82, 0
	v_mov_b32_e32 v81, 0
	v_mov_b32_e32 v80, 0
	v_mov_b32_e32 v71, 0
	v_mov_b32_e32 v70, 0
	v_mov_b32_e32 v69, 0
	v_mov_b32_e32 v68, 0
	v_mov_b32_e32 v67, 0
	v_mov_b32_e32 v66, 0
	v_mov_b32_e32 v65, 0
	v_mov_b32_e32 v64, 0
	v_mov_b32_e32 v63, 0
	v_mov_b32_e32 v62, 0
	v_mov_b32_e32 v61, 0
	v_mov_b32_e32 v60, 0
	v_mov_b32_e32 v59, 0
	v_mov_b32_e32 v58, 0
	v_mov_b32_e32 v57, 0
	v_mov_b32_e32 v56, 0
	v_mov_b32_e32 v47, 0
	v_mov_b32_e32 v46, 0
	v_mov_b32_e32 v45, 0
	v_mov_b32_e32 v44, 0
	v_mov_b32_e32 v43, 0
	v_mov_b32_e32 v42, 0
	v_mov_b32_e32 v41, 0
	v_mov_b32_e32 v40, 0
	v_mov_b32_e32 v31, 0
	v_mov_b32_e32 v30, 0
	v_mov_b32_e32 v29, 0
	v_mov_b32_e32 v28, 0
	v_mov_b32_e32 v27, 0
	v_mov_b32_e32 v26, 0
	v_mov_b32_e32 v25, 0
	v_mov_b32_e32 v24, 0
	v_mov_b32_e32 v15, 0
	v_mov_b32_e32 v14, 0
	v_mov_b32_e32 v13, 0
	v_mov_b32_e32 v12, 0
	v_mov_b32_e32 v11, 0
	v_mov_b32_e32 v10, 0
	v_mov_b32_e32 v9, 0
	v_mov_b32_e32 v8, 0
	v_mov_b32_e32 v55, 0
	v_mov_b32_e32 v54, 0
	v_mov_b32_e32 v53, 0
	v_mov_b32_e32 v52, 0
	v_mov_b32_e32 v51, 0
	v_mov_b32_e32 v50, 0
	v_mov_b32_e32 v49, 0
	v_mov_b32_e32 v48, 0
	v_mov_b32_e32 v39, 0
	v_mov_b32_e32 v38, 0
	v_mov_b32_e32 v37, 0
	v_mov_b32_e32 v36, 0
	v_mov_b32_e32 v35, 0
	v_mov_b32_e32 v34, 0
	v_mov_b32_e32 v33, 0
	v_mov_b32_e32 v32, 0
	v_mov_b32_e32 v23, 0
	v_mov_b32_e32 v22, 0
	v_mov_b32_e32 v21, 0
	v_mov_b32_e32 v20, 0
	v_mov_b32_e32 v19, 0
	v_mov_b32_e32 v18, 0
	v_mov_b32_e32 v17, 0
	v_mov_b32_e32 v16, 0
	v_mov_b32_e32 v7, 0
	v_mov_b32_e32 v6, 0
	v_mov_b32_e32 v5, 0
	v_mov_b32_e32 v4, 0
	v_mov_b32_e32 v3, 0
	v_mov_b32_e32 v2, 0
	v_mov_b32_e32 v1, 0
	v_mov_b32_e32 v0, 0
	s_cbranch_vccnz .LBB0_251
	s_add_u32 s0, s64, 0x40080
	s_addc_u32 s1, s65, 0
	s_add_u32 s3, s62, 0x100
	s_addc_u32 s27, s63, 0
	s_mov_b32 s41, 0

.LBB0_315:
	v_mov_b32_e32 v127, 0
	s_andn2_b64 vcc, exec, s[48:49]
	v_mov_b32_e32 v126, v127
	v_mov_b32_e32 v125, v127
	v_mov_b32_e32 v124, v127
	v_mov_b32_e32 v123, v127
	v_mov_b32_e32 v122, v127
	v_mov_b32_e32 v121, v127
	v_mov_b32_e32 v120, v127
	v_mov_b32_e32 v111, v127
	v_mov_b32_e32 v110, v127
	v_mov_b32_e32 v109, v127
	v_mov_b32_e32 v108, v127
	v_mov_b32_e32 v107, v127
	v_mov_b32_e32 v106, v127
	v_mov_b32_e32 v105, v127
	v_mov_b32_e32 v104, v127
	v_mov_b32_e32 v95, v127
	v_mov_b32_e32 v94, v127
	v_mov_b32_e32 v93, v127
	v_mov_b32_e32 v92, v127
	v_mov_b32_e32 v91, v127
	v_mov_b32_e32 v90, v127
	v_mov_b32_e32 v89, v127
	v_mov_b32_e32 v88, v127
	v_mov_b32_e32 v79, v127
	v_mov_b32_e32 v78, v127
	v_mov_b32_e32 v77, v127
	v_mov_b32_e32 v76, v127
	v_mov_b32_e32 v75, v127
	v_mov_b32_e32 v74, v127
	v_mov_b32_e32 v73, v127
	v_mov_b32_e32 v72, v127
	v_mov_b32_e32 v119, v127
	v_mov_b32_e32 v118, v127
	v_mov_b32_e32 v117, v127
	v_mov_b32_e32 v116, v127
	v_mov_b32_e32 v115, v127
	v_mov_b32_e32 v114, v127
	v_mov_b32_e32 v113, v127
	v_mov_b32_e32 v112, v127
	v_mov_b32_e32 v103, v127
	v_mov_b32_e32 v102, v127
	v_mov_b32_e32 v101, v127
	v_mov_b32_e32 v100, v127
	v_mov_b32_e32 v99, v127
	v_mov_b32_e32 v98, v127
	v_mov_b32_e32 v97, v127
	v_mov_b32_e32 v96, v127
	v_mov_b32_e32 v87, v127
	v_mov_b32_e32 v86, v127
	v_mov_b32_e32 v85, v127
	v_mov_b32_e32 v84, v127
	v_mov_b32_e32 v83, v127
	v_mov_b32_e32 v82, v127
	v_mov_b32_e32 v81, v127
	v_mov_b32_e32 v80, v127
	v_mov_b32_e32 v71, v127
	v_mov_b32_e32 v70, v127
	v_mov_b32_e32 v69, v127
	v_mov_b32_e32 v68, v127
	v_mov_b32_e32 v67, v127
	v_mov_b32_e32 v66, v127
	v_mov_b32_e32 v65, v127
	v_mov_b32_e32 v64, v127
	v_mov_b32_e32 v63, v127
	v_mov_b32_e32 v62, v127
	v_mov_b32_e32 v61, v127
	v_mov_b32_e32 v60, v127
	v_mov_b32_e32 v59, v127
	v_mov_b32_e32 v58, v127
	v_mov_b32_e32 v57, v127
	v_mov_b32_e32 v56, v127
	v_mov_b32_e32 v47, v127
	v_mov_b32_e32 v46, v127
	v_mov_b32_e32 v45, v127
	v_mov_b32_e32 v44, v127
	v_mov_b32_e32 v43, v127
	v_mov_b32_e32 v42, v127
	v_mov_b32_e32 v41, v127
	v_mov_b32_e32 v40, v127
	v_mov_b32_e32 v31, v127
	v_mov_b32_e32 v30, v127
	v_mov_b32_e32 v29, v127
	v_mov_b32_e32 v28, v127
	v_mov_b32_e32 v27, v127
	v_mov_b32_e32 v26, v127
	v_mov_b32_e32 v25, v127
	v_mov_b32_e32 v24, v127
	v_mov_b32_e32 v15, v127
	v_mov_b32_e32 v14, v127
	v_mov_b32_e32 v13, v127
	v_mov_b32_e32 v12, v127
	v_mov_b32_e32 v11, v127
	v_mov_b32_e32 v10, v127
	v_mov_b32_e32 v9, v127
	v_mov_b32_e32 v8, v127
	v_mov_b32_e32 v55, v127
	v_mov_b32_e32 v54, v127
	v_mov_b32_e32 v53, v127
	v_mov_b32_e32 v52, v127
	v_mov_b32_e32 v51, v127
	v_mov_b32_e32 v50, v127
	v_mov_b32_e32 v49, v127
	v_mov_b32_e32 v48, v127
	v_mov_b32_e32 v39, v127
	v_mov_b32_e32 v38, v127
	v_mov_b32_e32 v37, v127
	v_mov_b32_e32 v36, v127
	v_mov_b32_e32 v35, v127
	v_mov_b32_e32 v34, v127
	v_mov_b32_e32 v33, v127
	v_mov_b32_e32 v32, v127
	v_mov_b32_e32 v23, v127
	v_mov_b32_e32 v22, v127
	v_mov_b32_e32 v21, v127
	v_mov_b32_e32 v20, v127
	v_mov_b32_e32 v19, v127
	v_mov_b32_e32 v18, v127
	v_mov_b32_e32 v17, v127
	v_mov_b32_e32 v16, v127
	v_mov_b32_e32 v7, v127
	v_mov_b32_e32 v6, v127
	v_mov_b32_e32 v5, v127
	v_mov_b32_e32 v4, v127
	v_mov_b32_e32 v3, v127
	v_mov_b32_e32 v2, v127
	v_mov_b32_e32 v1, v127
	v_mov_b32_e32 v0, v127
	s_cbranch_vccnz .LBB0_318
	s_add_u32 s2, s2, 0x40080
	s_addc_u32 s3, s3, 0
	s_add_u32 s55, s20, 0x100
	s_addc_u32 s57, s21, 0
	s_mov_b32 s20, 0

.LBB0_376:
	s_ashr_i32 s63, s62, 31
	s_lshl_b64 s[26:27], s[62:63], 19
	v_readlane_b32 s40, v254, 43
	v_readlane_b32 s41, v254, 44
	s_add_u32 s66, s40, s26
	s_addc_u32 s67, s41, s27
	s_ashr_i32 s65, s64, 31
	s_lshl_b64 s[26:27], s[64:65], 19
	s_add_u32 s68, s34, s26
	v_mov_b32_e32 v159, 0
	s_addc_u32 s69, s42, s27
	s_andn2_b64 vcc, exec, s[58:59]
	v_mov_b32_e32 v158, v159
	v_mov_b32_e32 v157, v159
	v_mov_b32_e32 v156, v159
	v_mov_b32_e32 v155, v159
	v_mov_b32_e32 v154, v159
	v_mov_b32_e32 v153, v159
	v_mov_b32_e32 v152, v159
	v_mov_b32_e32 v143, v159
	v_mov_b32_e32 v142, v159
	v_mov_b32_e32 v141, v159
	v_mov_b32_e32 v140, v159
	v_mov_b32_e32 v139, v159
	v_mov_b32_e32 v138, v159
	v_mov_b32_e32 v137, v159
	v_mov_b32_e32 v136, v159
	v_mov_b32_e32 v127, v159
	v_mov_b32_e32 v126, v159
	v_mov_b32_e32 v125, v159
	v_mov_b32_e32 v124, v159
	v_mov_b32_e32 v123, v159
	v_mov_b32_e32 v122, v159
	v_mov_b32_e32 v121, v159
	v_mov_b32_e32 v120, v159
	v_mov_b32_e32 v95, v159
	v_mov_b32_e32 v94, v159
	v_mov_b32_e32 v93, v159
	v_mov_b32_e32 v92, v159
	v_mov_b32_e32 v83, v159
	v_mov_b32_e32 v82, v159
	v_mov_b32_e32 v81, v159
	v_mov_b32_e32 v80, v159
	v_mov_b32_e32 v151, v159
	v_mov_b32_e32 v150, v159
	v_mov_b32_e32 v149, v159
	v_mov_b32_e32 v148, v159
	v_mov_b32_e32 v147, v159
	v_mov_b32_e32 v146, v159
	v_mov_b32_e32 v145, v159
	v_mov_b32_e32 v144, v159
	v_mov_b32_e32 v135, v159
	v_mov_b32_e32 v134, v159
	v_mov_b32_e32 v133, v159
	v_mov_b32_e32 v132, v159
	v_mov_b32_e32 v131, v159
	v_mov_b32_e32 v130, v159
	v_mov_b32_e32 v129, v159
	v_mov_b32_e32 v128, v159
	v_mov_b32_e32 v119, v159
	v_mov_b32_e32 v118, v159
	v_mov_b32_e32 v117, v159
	v_mov_b32_e32 v116, v159
	v_mov_b32_e32 v115, v159
	v_mov_b32_e32 v114, v159
	v_mov_b32_e32 v113, v159
	v_mov_b32_e32 v112, v159
	v_mov_b32_e32 v71, v159
	v_mov_b32_e32 v70, v159
	v_mov_b32_e32 v69, v159
	v_mov_b32_e32 v68, v159
	v_mov_b32_e32 v67, v159
	v_mov_b32_e32 v66, v159
	v_mov_b32_e32 v65, v159
	v_mov_b32_e32 v64, v159
	v_mov_b32_e32 v63, v159
	v_mov_b32_e32 v62, v159
	v_mov_b32_e32 v61, v159
	v_mov_b32_e32 v60, v159
	v_mov_b32_e32 v59, v159
	v_mov_b32_e32 v58, v159
	v_mov_b32_e32 v57, v159
	v_mov_b32_e32 v56, v159
	v_mov_b32_e32 v47, v159
	v_mov_b32_e32 v46, v159
	v_mov_b32_e32 v45, v159
	v_mov_b32_e32 v44, v159
	v_mov_b32_e32 v43, v159
	v_mov_b32_e32 v42, v159
	v_mov_b32_e32 v41, v159
	v_mov_b32_e32 v40, v159
	v_mov_b32_e32 v31, v159
	v_mov_b32_e32 v30, v159
	v_mov_b32_e32 v29, v159
	v_mov_b32_e32 v28, v159
	v_mov_b32_e32 v27, v159
	v_mov_b32_e32 v26, v159
	v_mov_b32_e32 v25, v159
	v_mov_b32_e32 v24, v159
	v_mov_b32_e32 v15, v159
	v_mov_b32_e32 v14, v159
	v_mov_b32_e32 v13, v159
	v_mov_b32_e32 v12, v159
	v_mov_b32_e32 v11, v159
	v_mov_b32_e32 v10, v159
	v_mov_b32_e32 v9, v159
	v_mov_b32_e32 v8, v159
	v_mov_b32_e32 v55, v159
	v_mov_b32_e32 v54, v159
	v_mov_b32_e32 v53, v159
	v_mov_b32_e32 v52, v159
	v_mov_b32_e32 v51, v159
	v_mov_b32_e32 v50, v159
	v_mov_b32_e32 v49, v159
	v_mov_b32_e32 v48, v159
	v_mov_b32_e32 v39, v159
	v_mov_b32_e32 v38, v159
	v_mov_b32_e32 v37, v159
	v_mov_b32_e32 v36, v159
	v_mov_b32_e32 v35, v159
	v_mov_b32_e32 v34, v159
	v_mov_b32_e32 v33, v159
	v_mov_b32_e32 v32, v159
	v_mov_b32_e32 v23, v159
	v_mov_b32_e32 v22, v159
	v_mov_b32_e32 v21, v159
	v_mov_b32_e32 v20, v159
	v_mov_b32_e32 v19, v159
	v_mov_b32_e32 v18, v159
	v_mov_b32_e32 v17, v159
	v_mov_b32_e32 v16, v159
	v_mov_b32_e32 v7, v159
	v_mov_b32_e32 v6, v159
	v_mov_b32_e32 v5, v159
	v_mov_b32_e32 v4, v159
	v_mov_b32_e32 v3, v159
	v_mov_b32_e32 v2, v159
	v_mov_b32_e32 v1, v159
	v_mov_b32_e32 v0, v159
	s_cbranch_vccnz .LBB0_379
	s_and_b64 s[26:27], s[38:39], exec
	s_cselect_b32 s1, s67, s21
	s_cselect_b32 s40, s66, s20
	s_cselect_b32 s41, s69, s23
	s_cselect_b32 s44, s68, s22
	s_add_u32 s20, s20, 0x40080
	s_addc_u32 s21, s21, 0
	s_add_u32 s45, s22, 0x100
	s_addc_u32 s63, s23, 0
	s_mov_b32 s22, 0

.LBB0_442:
	s_ashr_i32 s51, s50, 31
	s_lshl_b64 s[20:21], s[50:51], 19
	v_readlane_b32 s42, v254, 57
	v_readlane_b32 s43, v254, 58
	s_add_u32 s54, s42, s20
	s_addc_u32 s55, s43, s21
	s_ashr_i32 s53, s52, 31
	s_lshl_b64 s[20:21], s[52:53], 19
	s_add_u32 s56, s34, s20
	v_mov_b32_e32 v127, 0
	s_addc_u32 s57, s60, s21
	s_andn2_b64 vcc, exec, s[46:47]
	v_mov_b32_e32 v126, v127
	v_mov_b32_e32 v125, v127
	v_mov_b32_e32 v124, v127
	v_mov_b32_e32 v123, v127
	v_mov_b32_e32 v122, v127
	v_mov_b32_e32 v121, v127
	v_mov_b32_e32 v120, v127
	v_mov_b32_e32 v111, v127
	v_mov_b32_e32 v110, v127
	v_mov_b32_e32 v109, v127
	v_mov_b32_e32 v108, v127
	v_mov_b32_e32 v107, v127
	v_mov_b32_e32 v106, v127
	v_mov_b32_e32 v105, v127
	v_mov_b32_e32 v104, v127
	v_mov_b32_e32 v95, v127
	v_mov_b32_e32 v94, v127
	v_mov_b32_e32 v93, v127
	v_mov_b32_e32 v92, v127
	v_mov_b32_e32 v91, v127
	v_mov_b32_e32 v90, v127
	v_mov_b32_e32 v89, v127
	v_mov_b32_e32 v88, v127
	v_mov_b32_e32 v79, v127
	v_mov_b32_e32 v78, v127
	v_mov_b32_e32 v77, v127
	v_mov_b32_e32 v76, v127
	v_mov_b32_e32 v75, v127
	v_mov_b32_e32 v74, v127
	v_mov_b32_e32 v73, v127
	v_mov_b32_e32 v72, v127
	v_mov_b32_e32 v119, v127
	v_mov_b32_e32 v118, v127
	v_mov_b32_e32 v117, v127
	v_mov_b32_e32 v116, v127
	v_mov_b32_e32 v115, v127
	v_mov_b32_e32 v114, v127
	v_mov_b32_e32 v113, v127
	v_mov_b32_e32 v112, v127
	v_mov_b32_e32 v103, v127
	v_mov_b32_e32 v102, v127
	v_mov_b32_e32 v101, v127
	v_mov_b32_e32 v100, v127
	v_mov_b32_e32 v99, v127
	v_mov_b32_e32 v98, v127
	v_mov_b32_e32 v97, v127
	v_mov_b32_e32 v96, v127
	v_mov_b32_e32 v87, v127
	v_mov_b32_e32 v86, v127
	v_mov_b32_e32 v85, v127
	v_mov_b32_e32 v84, v127
	v_mov_b32_e32 v83, v127
	v_mov_b32_e32 v82, v127
	v_mov_b32_e32 v81, v127
	v_mov_b32_e32 v80, v127
	v_mov_b32_e32 v71, v127
	v_mov_b32_e32 v70, v127
	v_mov_b32_e32 v69, v127
	v_mov_b32_e32 v68, v127
	v_mov_b32_e32 v67, v127
	v_mov_b32_e32 v66, v127
	v_mov_b32_e32 v65, v127
	v_mov_b32_e32 v64, v127
	v_mov_b32_e32 v63, v127
	v_mov_b32_e32 v62, v127
	v_mov_b32_e32 v61, v127
	v_mov_b32_e32 v60, v127
	v_mov_b32_e32 v59, v127
	v_mov_b32_e32 v58, v127
	v_mov_b32_e32 v57, v127
	v_mov_b32_e32 v56, v127
	v_mov_b32_e32 v47, v127
	v_mov_b32_e32 v46, v127
	v_mov_b32_e32 v45, v127
	v_mov_b32_e32 v44, v127
	v_mov_b32_e32 v43, v127
	v_mov_b32_e32 v42, v127
	v_mov_b32_e32 v41, v127
	v_mov_b32_e32 v40, v127
	v_mov_b32_e32 v31, v127
	v_mov_b32_e32 v30, v127
	v_mov_b32_e32 v29, v127
	v_mov_b32_e32 v28, v127
	v_mov_b32_e32 v27, v127
	v_mov_b32_e32 v26, v127
	v_mov_b32_e32 v25, v127
	v_mov_b32_e32 v24, v127
	v_mov_b32_e32 v15, v127
	v_mov_b32_e32 v14, v127
	v_mov_b32_e32 v13, v127
	v_mov_b32_e32 v12, v127
	v_mov_b32_e32 v11, v127
	v_mov_b32_e32 v10, v127
	v_mov_b32_e32 v9, v127
	v_mov_b32_e32 v8, v127
	v_mov_b32_e32 v55, v127
	v_mov_b32_e32 v54, v127
	v_mov_b32_e32 v53, v127
	v_mov_b32_e32 v52, v127
	v_mov_b32_e32 v51, v127
	v_mov_b32_e32 v50, v127
	v_mov_b32_e32 v49, v127
	v_mov_b32_e32 v48, v127
	v_mov_b32_e32 v39, v127
	v_mov_b32_e32 v38, v127
	v_mov_b32_e32 v37, v127
	v_mov_b32_e32 v36, v127
	v_mov_b32_e32 v35, v127
	v_mov_b32_e32 v34, v127
	v_mov_b32_e32 v33, v127
	v_mov_b32_e32 v32, v127
	v_mov_b32_e32 v23, v127
	v_mov_b32_e32 v22, v127
	v_mov_b32_e32 v21, v127
	v_mov_b32_e32 v20, v127
	v_mov_b32_e32 v19, v127
	v_mov_b32_e32 v18, v127
	v_mov_b32_e32 v17, v127
	v_mov_b32_e32 v16, v127
	v_mov_b32_e32 v7, v127
	v_mov_b32_e32 v6, v127
	v_mov_b32_e32 v5, v127
	v_mov_b32_e32 v4, v127
	s_waitcnt lgkmcnt(0)
	v_mov_b32_e32 v3, v127
	v_mov_b32_e32 v2, v127
	v_mov_b32_e32 v1, v127
	v_mov_b32_e32 v0, v127
	s_cbranch_vccnz .LBB0_445
	s_and_b64 s[20:21], s[38:39], exec
	s_cselect_b32 s41, s55, s1
	s_cselect_b32 s42, s54, s0
	s_cselect_b32 s43, s57, s3
	s_cselect_b32 s51, s56, s2
	s_add_u32 s0, s0, 0x40080
	s_addc_u32 s1, s1, 0
	s_add_u32 s53, s2, 0x100
	s_addc_u32 s58, s3, 0
	s_mov_b32 s2, 0

.LBB0_489:
	s_ashr_i32 s49, s48, 31
	s_lshl_b64 s[22:23], s[48:49], 19
	v_readlane_b32 s40, v254, 57
	v_readlane_b32 s41, v254, 58
	s_add_u32 s52, s40, s22
	s_addc_u32 s53, s41, s23
	s_ashr_i32 s51, s50, 31
	s_lshl_b64 s[22:23], s[50:51], 19
	s_add_u32 s54, s34, s22
	v_mov_b32_e32 v127, 0
	s_addc_u32 s55, s60, s23
	s_andn2_b64 vcc, exec, s[44:45]
	v_mov_b32_e32 v126, v127
	v_mov_b32_e32 v125, v127
	v_mov_b32_e32 v124, v127
	v_mov_b32_e32 v123, v127
	v_mov_b32_e32 v122, v127
	v_mov_b32_e32 v121, v127
	v_mov_b32_e32 v120, v127
	v_mov_b32_e32 v111, v127
	v_mov_b32_e32 v110, v127
	v_mov_b32_e32 v109, v127
	v_mov_b32_e32 v108, v127
	v_mov_b32_e32 v107, v127
	v_mov_b32_e32 v106, v127
	v_mov_b32_e32 v105, v127
	v_mov_b32_e32 v104, v127
	v_mov_b32_e32 v95, v127
	v_mov_b32_e32 v94, v127
	v_mov_b32_e32 v93, v127
	v_mov_b32_e32 v92, v127
	v_mov_b32_e32 v91, v127
	v_mov_b32_e32 v90, v127
	v_mov_b32_e32 v89, v127
	v_mov_b32_e32 v88, v127
	v_mov_b32_e32 v79, v127
	v_mov_b32_e32 v78, v127
	v_mov_b32_e32 v77, v127
	v_mov_b32_e32 v76, v127
	v_mov_b32_e32 v75, v127
	v_mov_b32_e32 v74, v127
	v_mov_b32_e32 v73, v127
	v_mov_b32_e32 v72, v127
	v_mov_b32_e32 v119, v127
	v_mov_b32_e32 v118, v127
	v_mov_b32_e32 v117, v127
	v_mov_b32_e32 v116, v127
	v_mov_b32_e32 v115, v127
	v_mov_b32_e32 v114, v127
	v_mov_b32_e32 v113, v127
	v_mov_b32_e32 v112, v127
	v_mov_b32_e32 v103, v127
	v_mov_b32_e32 v102, v127
	v_mov_b32_e32 v101, v127
	v_mov_b32_e32 v100, v127
	v_mov_b32_e32 v99, v127
	v_mov_b32_e32 v98, v127
	v_mov_b32_e32 v97, v127
	v_mov_b32_e32 v96, v127
	v_mov_b32_e32 v87, v127
	v_mov_b32_e32 v86, v127
	v_mov_b32_e32 v85, v127
	v_mov_b32_e32 v84, v127
	v_mov_b32_e32 v83, v127
	v_mov_b32_e32 v82, v127
	v_mov_b32_e32 v81, v127
	v_mov_b32_e32 v80, v127
	v_mov_b32_e32 v71, v127
	v_mov_b32_e32 v70, v127
	v_mov_b32_e32 v69, v127
	v_mov_b32_e32 v68, v127
	v_mov_b32_e32 v67, v127
	v_mov_b32_e32 v66, v127
	v_mov_b32_e32 v65, v127
	v_mov_b32_e32 v64, v127
	v_mov_b32_e32 v63, v127
	v_mov_b32_e32 v62, v127
	v_mov_b32_e32 v61, v127
	v_mov_b32_e32 v60, v127
	v_mov_b32_e32 v59, v127
	v_mov_b32_e32 v58, v127
	v_mov_b32_e32 v57, v127
	v_mov_b32_e32 v56, v127
	v_mov_b32_e32 v47, v127
	v_mov_b32_e32 v46, v127
	v_mov_b32_e32 v45, v127
	v_mov_b32_e32 v44, v127
	v_mov_b32_e32 v43, v127
	v_mov_b32_e32 v42, v127
	v_mov_b32_e32 v41, v127
	v_mov_b32_e32 v40, v127
	v_mov_b32_e32 v31, v127
	v_mov_b32_e32 v30, v127
	v_mov_b32_e32 v29, v127
	v_mov_b32_e32 v28, v127
	v_mov_b32_e32 v27, v127
	v_mov_b32_e32 v26, v127
	v_mov_b32_e32 v25, v127
	v_mov_b32_e32 v24, v127
	v_mov_b32_e32 v15, v127
	v_mov_b32_e32 v14, v127
	v_mov_b32_e32 v13, v127
	v_mov_b32_e32 v12, v127
	v_mov_b32_e32 v11, v127
	v_mov_b32_e32 v10, v127
	v_mov_b32_e32 v9, v127
	v_mov_b32_e32 v8, v127
	v_mov_b32_e32 v55, v127
	v_mov_b32_e32 v54, v127
	v_mov_b32_e32 v53, v127
	v_mov_b32_e32 v52, v127
	v_mov_b32_e32 v51, v127
	v_mov_b32_e32 v50, v127
	v_mov_b32_e32 v49, v127
	v_mov_b32_e32 v48, v127
	v_mov_b32_e32 v39, v127
	v_mov_b32_e32 v38, v127
	v_mov_b32_e32 v37, v127
	v_mov_b32_e32 v36, v127
	v_mov_b32_e32 v35, v127
	v_mov_b32_e32 v34, v127
	v_mov_b32_e32 v33, v127
	v_mov_b32_e32 v32, v127
	v_mov_b32_e32 v23, v127
	v_mov_b32_e32 v22, v127
	v_mov_b32_e32 v21, v127
	v_mov_b32_e32 v20, v127
	v_mov_b32_e32 v19, v127
	v_mov_b32_e32 v18, v127
	v_mov_b32_e32 v17, v127
	v_mov_b32_e32 v16, v127
	v_mov_b32_e32 v7, v127
	v_mov_b32_e32 v6, v127
	v_mov_b32_e32 v5, v127
	v_mov_b32_e32 v4, v127
	s_waitcnt lgkmcnt(0)
	v_mov_b32_e32 v3, v127
	v_mov_b32_e32 v2, v127
	v_mov_b32_e32 v1, v127
	v_mov_b32_e32 v0, v127
	s_cbranch_vccnz .LBB0_492
	s_and_b64 s[22:23], s[38:39], exec
	s_cselect_b32 s1, s53, s3
	s_cselect_b32 s25, s52, s2
	s_cselect_b32 s40, s55, s21
	s_cselect_b32 s41, s54, s20
	s_add_u32 s2, s2, 0x40080
	s_addc_u32 s3, s3, 0
	s_add_u32 s49, s20, 0x100
	s_addc_u32 s51, s21, 0
	s_mov_b32 s20, 0

.LBB0_535:
	s_ashr_i32 s47, s46, 31
	s_lshl_b64 s[22:23], s[46:47], 19
	s_add_u32 s48, s52, s22
	v_mov_b32_e32 v127, 0
	s_addc_u32 s49, s53, s23
	s_andn2_b64 vcc, exec, s[42:43]
	v_mov_b32_e32 v126, v127
	v_mov_b32_e32 v125, v127
	v_mov_b32_e32 v124, v127
	v_mov_b32_e32 v123, v127
	v_mov_b32_e32 v122, v127
	v_mov_b32_e32 v121, v127
	v_mov_b32_e32 v120, v127
	v_mov_b32_e32 v111, v127
	v_mov_b32_e32 v110, v127
	v_mov_b32_e32 v109, v127
	v_mov_b32_e32 v108, v127
	v_mov_b32_e32 v107, v127
	v_mov_b32_e32 v106, v127
	v_mov_b32_e32 v105, v127
	v_mov_b32_e32 v104, v127
	v_mov_b32_e32 v95, v127
	v_mov_b32_e32 v94, v127
	v_mov_b32_e32 v93, v127
	v_mov_b32_e32 v92, v127
	v_mov_b32_e32 v91, v127
	v_mov_b32_e32 v90, v127
	v_mov_b32_e32 v89, v127
	v_mov_b32_e32 v88, v127
	v_mov_b32_e32 v79, v127
	v_mov_b32_e32 v78, v127
	v_mov_b32_e32 v77, v127
	v_mov_b32_e32 v76, v127
	v_mov_b32_e32 v75, v127
	v_mov_b32_e32 v74, v127
	v_mov_b32_e32 v73, v127
	v_mov_b32_e32 v72, v127
	v_mov_b32_e32 v119, v127
	v_mov_b32_e32 v118, v127
	v_mov_b32_e32 v117, v127
	v_mov_b32_e32 v116, v127
	v_mov_b32_e32 v115, v127
	v_mov_b32_e32 v114, v127
	v_mov_b32_e32 v113, v127
	v_mov_b32_e32 v112, v127
	v_mov_b32_e32 v103, v127
	v_mov_b32_e32 v102, v127
	v_mov_b32_e32 v101, v127
	v_mov_b32_e32 v100, v127
	v_mov_b32_e32 v99, v127
	v_mov_b32_e32 v98, v127
	v_mov_b32_e32 v97, v127
	v_mov_b32_e32 v96, v127
	v_mov_b32_e32 v87, v127
	v_mov_b32_e32 v86, v127
	v_mov_b32_e32 v85, v127
	v_mov_b32_e32 v84, v127
	v_mov_b32_e32 v83, v127
	v_mov_b32_e32 v82, v127
	v_mov_b32_e32 v81, v127
	v_mov_b32_e32 v80, v127
	v_mov_b32_e32 v71, v127
	v_mov_b32_e32 v70, v127
	v_mov_b32_e32 v69, v127
	v_mov_b32_e32 v68, v127
	v_mov_b32_e32 v67, v127
	v_mov_b32_e32 v66, v127
	v_mov_b32_e32 v65, v127
	v_mov_b32_e32 v64, v127
	v_mov_b32_e32 v63, v127
	v_mov_b32_e32 v62, v127
	v_mov_b32_e32 v61, v127
	v_mov_b32_e32 v60, v127
	v_mov_b32_e32 v59, v127
	v_mov_b32_e32 v58, v127
	v_mov_b32_e32 v57, v127
	v_mov_b32_e32 v56, v127
	v_mov_b32_e32 v47, v127
	v_mov_b32_e32 v46, v127
	v_mov_b32_e32 v45, v127
	v_mov_b32_e32 v44, v127
	v_mov_b32_e32 v43, v127
	v_mov_b32_e32 v42, v127
	v_mov_b32_e32 v41, v127
	v_mov_b32_e32 v40, v127
	v_mov_b32_e32 v31, v127
	v_mov_b32_e32 v30, v127
	v_mov_b32_e32 v29, v127
	v_mov_b32_e32 v28, v127
	v_mov_b32_e32 v27, v127
	v_mov_b32_e32 v26, v127
	v_mov_b32_e32 v25, v127
	v_mov_b32_e32 v24, v127
	v_mov_b32_e32 v15, v127
	v_mov_b32_e32 v14, v127
	v_mov_b32_e32 v13, v127
	v_mov_b32_e32 v12, v127
	v_mov_b32_e32 v11, v127
	v_mov_b32_e32 v10, v127
	v_mov_b32_e32 v9, v127
	v_mov_b32_e32 v8, v127
	v_mov_b32_e32 v55, v127
	v_mov_b32_e32 v54, v127
	v_mov_b32_e32 v53, v127
	v_mov_b32_e32 v52, v127
	v_mov_b32_e32 v51, v127
	v_mov_b32_e32 v50, v127
	v_mov_b32_e32 v49, v127
	v_mov_b32_e32 v48, v127
	v_mov_b32_e32 v39, v127
	v_mov_b32_e32 v38, v127
	v_mov_b32_e32 v37, v127
	v_mov_b32_e32 v36, v127
	v_mov_b32_e32 v35, v127
	v_mov_b32_e32 v34, v127
	v_mov_b32_e32 v33, v127
	v_mov_b32_e32 v32, v127
	v_mov_b32_e32 v23, v127
	v_mov_b32_e32 v22, v127
	v_mov_b32_e32 v21, v127
	v_mov_b32_e32 v20, v127
	v_mov_b32_e32 v19, v127
	v_mov_b32_e32 v18, v127
	v_mov_b32_e32 v17, v127
	v_mov_b32_e32 v16, v127
	v_mov_b32_e32 v3, v127
	v_mov_b32_e32 v2, v127
	v_mov_b32_e32 v1, v127
	v_mov_b32_e32 v0, v127
	v_mov_b32_e32 v7, v127
	v_mov_b32_e32 v6, v127
	v_mov_b32_e32 v5, v127
	v_mov_b32_e32 v4, v127
	s_cbranch_vccnz .LBB0_539
	s_and_b64 s[22:23], s[38:39], exec
	s_cselect_b32 s3, s49, s21
	s_cselect_b32 s47, s48, s20
	s_add_u32 s66, s20, 0x100
	s_addc_u32 s67, s21, 0
	s_add_u32 s20, s20, 0x40080
	s_addc_u32 s21, s21, 0
	v_lshl_add_u64 v[138:139], s[20:21], 0, v[134:135]
	v_lshl_add_u64 v[140:141], s[20:21], 0, v[136:137]
	s_mov_b32 s26, 0
	s_mov_b64 s[20:21], 0

.LBB0_572:
	s_ashr_i32 s43, s42, 31
	s_ashr_i32 s45, s44, 31
	s_lshl_b64 s[46:47], s[44:45], 18
	s_lshl_b64 s[48:49], s[42:43], 22
	s_add_u32 s3, s78, s48
	s_addc_u32 s21, s79, s49
	s_add_u32 s46, s3, s46
	s_addc_u32 s47, s21, s47
	s_ashr_i32 s3, s67, 31
	s_add_u32 s48, s67, s42
	s_addc_u32 s49, s3, s43
	s_lshl_b64 s[48:49], s[48:49], 18
	s_add_u32 s48, s52, s48
	v_mov_b32_e32 v127, 0
	s_addc_u32 s49, s53, s49
	s_andn2_b64 vcc, exec, s[24:25]
	v_mov_b32_e32 v126, v127
	v_mov_b32_e32 v125, v127
	v_mov_b32_e32 v124, v127
	v_mov_b32_e32 v123, v127
	v_mov_b32_e32 v122, v127
	v_mov_b32_e32 v121, v127
	v_mov_b32_e32 v120, v127
	v_mov_b32_e32 v111, v127
	v_mov_b32_e32 v110, v127
	v_mov_b32_e32 v109, v127
	v_mov_b32_e32 v108, v127
	v_mov_b32_e32 v107, v127
	v_mov_b32_e32 v106, v127
	v_mov_b32_e32 v105, v127
	v_mov_b32_e32 v104, v127
	v_mov_b32_e32 v95, v127
	v_mov_b32_e32 v94, v127
	v_mov_b32_e32 v93, v127
	v_mov_b32_e32 v92, v127
	v_mov_b32_e32 v91, v127
	v_mov_b32_e32 v90, v127
	v_mov_b32_e32 v89, v127
	v_mov_b32_e32 v88, v127
	v_mov_b32_e32 v79, v127
	v_mov_b32_e32 v78, v127
	v_mov_b32_e32 v77, v127
	v_mov_b32_e32 v76, v127
	v_mov_b32_e32 v75, v127
	v_mov_b32_e32 v74, v127
	v_mov_b32_e32 v73, v127
	v_mov_b32_e32 v72, v127
	v_mov_b32_e32 v119, v127
	v_mov_b32_e32 v118, v127
	v_mov_b32_e32 v117, v127
	v_mov_b32_e32 v116, v127
	v_mov_b32_e32 v115, v127
	v_mov_b32_e32 v114, v127
	v_mov_b32_e32 v113, v127
	v_mov_b32_e32 v112, v127
	v_mov_b32_e32 v103, v127
	v_mov_b32_e32 v102, v127
	v_mov_b32_e32 v101, v127
	v_mov_b32_e32 v100, v127
	v_mov_b32_e32 v99, v127
	v_mov_b32_e32 v98, v127
	v_mov_b32_e32 v97, v127
	v_mov_b32_e32 v96, v127
	v_mov_b32_e32 v87, v127
	v_mov_b32_e32 v86, v127
	v_mov_b32_e32 v85, v127
	v_mov_b32_e32 v84, v127
	v_mov_b32_e32 v83, v127
	v_mov_b32_e32 v82, v127
	v_mov_b32_e32 v81, v127
	v_mov_b32_e32 v80, v127
	v_mov_b32_e32 v71, v127
	v_mov_b32_e32 v70, v127
	v_mov_b32_e32 v69, v127
	v_mov_b32_e32 v68, v127
	v_mov_b32_e32 v67, v127
	v_mov_b32_e32 v66, v127
	v_mov_b32_e32 v65, v127
	v_mov_b32_e32 v64, v127
	v_mov_b32_e32 v63, v127
	v_mov_b32_e32 v62, v127
	v_mov_b32_e32 v61, v127
	v_mov_b32_e32 v60, v127
	v_mov_b32_e32 v59, v127
	v_mov_b32_e32 v58, v127
	v_mov_b32_e32 v57, v127
	v_mov_b32_e32 v56, v127
	v_mov_b32_e32 v47, v127
	v_mov_b32_e32 v46, v127
	v_mov_b32_e32 v45, v127
	v_mov_b32_e32 v44, v127
	v_mov_b32_e32 v43, v127
	v_mov_b32_e32 v42, v127
	v_mov_b32_e32 v41, v127
	v_mov_b32_e32 v40, v127
	v_mov_b32_e32 v31, v127
	v_mov_b32_e32 v30, v127
	v_mov_b32_e32 v29, v127
	v_mov_b32_e32 v28, v127
	v_mov_b32_e32 v27, v127
	v_mov_b32_e32 v26, v127
	v_mov_b32_e32 v25, v127
	v_mov_b32_e32 v24, v127
	v_mov_b32_e32 v15, v127
	v_mov_b32_e32 v14, v127
	v_mov_b32_e32 v13, v127
	v_mov_b32_e32 v12, v127
	v_mov_b32_e32 v11, v127
	v_mov_b32_e32 v10, v127
	v_mov_b32_e32 v9, v127
	v_mov_b32_e32 v8, v127
	v_mov_b32_e32 v55, v127
	v_mov_b32_e32 v54, v127
	v_mov_b32_e32 v53, v127
	v_mov_b32_e32 v52, v127
	v_mov_b32_e32 v51, v127
	v_mov_b32_e32 v50, v127
	v_mov_b32_e32 v49, v127
	v_mov_b32_e32 v48, v127
	v_mov_b32_e32 v39, v127
	v_mov_b32_e32 v38, v127
	v_mov_b32_e32 v37, v127
	v_mov_b32_e32 v36, v127
	v_mov_b32_e32 v35, v127
	v_mov_b32_e32 v34, v127
	v_mov_b32_e32 v33, v127
	v_mov_b32_e32 v32, v127
	v_mov_b32_e32 v23, v127
	v_mov_b32_e32 v22, v127
	v_mov_b32_e32 v21, v127
	v_mov_b32_e32 v20, v127
	v_mov_b32_e32 v19, v127
	v_mov_b32_e32 v18, v127
	v_mov_b32_e32 v17, v127
	v_mov_b32_e32 v16, v127
	v_mov_b32_e32 v7, v127
	v_mov_b32_e32 v6, v127
	v_mov_b32_e32 v5, v127
	v_mov_b32_e32 v4, v127
	v_mov_b32_e32 v3, v127
	v_mov_b32_e32 v2, v127
	v_mov_b32_e32 v1, v127
	v_mov_b32_e32 v0, v127
	s_cbranch_vccnz .LBB0_575
	s_and_b64 s[50:51], s[38:39], exec
	s_cselect_b32 s3, s47, s23
	s_cselect_b32 s21, s46, s22
	s_cselect_b32 s43, s49, s27
	s_cselect_b32 s45, s48, s26
	s_add_u32 s22, s22, 0x20080
	s_addc_u32 s23, s23, 0
	s_add_u32 s68, s26, 0x100
	s_addc_u32 s69, s27, 0
	s_mov_b32 s26, 0

.LBB0_628:
	v_mov_b32_e32 v127, 0
	s_andn2_b64 vcc, exec, s[20:21]
	v_mov_b32_e32 v126, 0
	v_mov_b32_e32 v125, 0
	v_mov_b32_e32 v124, 0
	v_mov_b32_e32 v123, 0
	v_mov_b32_e32 v122, 0
	v_mov_b32_e32 v121, 0
	v_mov_b32_e32 v120, 0
	v_mov_b32_e32 v111, 0
	v_mov_b32_e32 v110, 0
	v_mov_b32_e32 v109, 0
	v_mov_b32_e32 v108, 0
	v_mov_b32_e32 v107, 0
	v_mov_b32_e32 v106, 0
	v_mov_b32_e32 v105, 0
	v_mov_b32_e32 v104, 0
	v_mov_b32_e32 v95, 0
	v_mov_b32_e32 v94, 0
	v_mov_b32_e32 v93, 0
	v_mov_b32_e32 v92, 0
	v_mov_b32_e32 v91, 0
	v_mov_b32_e32 v90, 0
	v_mov_b32_e32 v89, 0
	v_mov_b32_e32 v88, 0
	v_mov_b32_e32 v79, 0
	v_mov_b32_e32 v78, 0
	v_mov_b32_e32 v77, 0
	v_mov_b32_e32 v76, 0
	v_mov_b32_e32 v75, 0
	v_mov_b32_e32 v74, 0
	v_mov_b32_e32 v73, 0
	v_mov_b32_e32 v72, 0
	v_mov_b32_e32 v119, 0
	v_mov_b32_e32 v118, 0
	v_mov_b32_e32 v117, 0
	v_mov_b32_e32 v116, 0
	v_mov_b32_e32 v115, 0
	v_mov_b32_e32 v114, 0
	v_mov_b32_e32 v113, 0
	v_mov_b32_e32 v112, 0
	v_mov_b32_e32 v103, 0
	v_mov_b32_e32 v102, 0
	v_mov_b32_e32 v101, 0
	v_mov_b32_e32 v100, 0
	v_mov_b32_e32 v99, 0
	v_mov_b32_e32 v98, 0
	v_mov_b32_e32 v97, 0
	v_mov_b32_e32 v96, 0
	v_mov_b32_e32 v87, 0
	v_mov_b32_e32 v86, 0
	v_mov_b32_e32 v85, 0
	v_mov_b32_e32 v84, 0
	v_mov_b32_e32 v83, 0
	v_mov_b32_e32 v82, 0
	v_mov_b32_e32 v81, 0
	v_mov_b32_e32 v80, 0
	v_mov_b32_e32 v71, 0
	v_mov_b32_e32 v70, 0
	v_mov_b32_e32 v69, 0
	v_mov_b32_e32 v68, 0
	v_mov_b32_e32 v67, 0
	v_mov_b32_e32 v66, 0
	v_mov_b32_e32 v65, 0
	v_mov_b32_e32 v64, 0
	v_mov_b32_e32 v63, 0
	v_mov_b32_e32 v62, 0
	v_mov_b32_e32 v61, 0
	v_mov_b32_e32 v60, 0
	v_mov_b32_e32 v59, 0
	v_mov_b32_e32 v58, 0
	v_mov_b32_e32 v57, 0
	v_mov_b32_e32 v56, 0
	v_mov_b32_e32 v47, 0
	v_mov_b32_e32 v46, 0
	v_mov_b32_e32 v45, 0
	v_mov_b32_e32 v44, 0
	v_mov_b32_e32 v43, 0
	v_mov_b32_e32 v42, 0
	v_mov_b32_e32 v41, 0
	v_mov_b32_e32 v40, 0
	v_mov_b32_e32 v31, 0
	v_mov_b32_e32 v30, 0
	v_mov_b32_e32 v29, 0
	v_mov_b32_e32 v28, 0
	v_mov_b32_e32 v27, 0
	v_mov_b32_e32 v26, 0
	v_mov_b32_e32 v25, 0
	v_mov_b32_e32 v24, 0
	v_mov_b32_e32 v15, 0
	v_mov_b32_e32 v14, 0
	v_mov_b32_e32 v13, 0
	v_mov_b32_e32 v12, 0
	v_mov_b32_e32 v11, 0
	v_mov_b32_e32 v10, 0
	v_mov_b32_e32 v9, 0
	v_mov_b32_e32 v8, 0
	v_mov_b32_e32 v55, 0
	v_mov_b32_e32 v54, 0
	v_mov_b32_e32 v53, 0
	v_mov_b32_e32 v52, 0
	v_mov_b32_e32 v51, 0
	v_mov_b32_e32 v50, 0
	v_mov_b32_e32 v49, 0
	v_mov_b32_e32 v48, 0
	v_mov_b32_e32 v39, 0
	v_mov_b32_e32 v38, 0
	v_mov_b32_e32 v37, 0
	v_mov_b32_e32 v36, 0
	v_mov_b32_e32 v35, 0
	v_mov_b32_e32 v34, 0
	v_mov_b32_e32 v33, 0
	v_mov_b32_e32 v32, 0
	v_mov_b32_e32 v23, 0
	v_mov_b32_e32 v22, 0
	v_mov_b32_e32 v21, 0
	v_mov_b32_e32 v20, 0
	v_mov_b32_e32 v19, 0
	v_mov_b32_e32 v18, 0
	v_mov_b32_e32 v17, 0
	v_mov_b32_e32 v16, 0
	v_mov_b32_e32 v7, 0
	v_mov_b32_e32 v6, 0
	v_mov_b32_e32 v5, 0
	v_mov_b32_e32 v4, 0
	v_mov_b32_e32 v3, 0
	v_mov_b32_e32 v2, 0
	v_mov_b32_e32 v1, 0
	v_mov_b32_e32 v0, 0
	s_cbranch_vccnz .LBB0_631
	s_add_u32 s0, s50, 0x20080
	s_addc_u32 s1, s51, 0
	s_add_u32 s3, s48, 0x100
	s_addc_u32 s27, s49, 0
	s_mov_b32 s41, 0

.LBB0_851:
	s_ashr_i32 s53, s52, 31
	s_lshl_b64 s[26:27], s[52:53], 19
	v_readlane_b32 s40, v254, 43
	v_readlane_b32 s41, v254, 44
	s_add_u32 s56, s40, s26
	s_addc_u32 s57, s41, s27
	s_ashr_i32 s55, s54, 31
	s_lshl_b64 s[26:27], s[54:55], 19
	v_readlane_b32 s1, v254, 41
	s_add_u32 s58, s1, s26
	v_readlane_b32 s1, v254, 42
	v_mov_b32_e32 v159, 0
	s_addc_u32 s59, s1, s27
	s_andn2_b64 vcc, exec, s[48:49]
	v_mov_b32_e32 v158, v159
	v_mov_b32_e32 v157, v159
	v_mov_b32_e32 v156, v159
	v_mov_b32_e32 v155, v159
	v_mov_b32_e32 v154, v159
	v_mov_b32_e32 v153, v159
	v_mov_b32_e32 v152, v159
	v_mov_b32_e32 v143, v159
	v_mov_b32_e32 v142, v159
	v_mov_b32_e32 v141, v159
	v_mov_b32_e32 v140, v159
	v_mov_b32_e32 v139, v159
	v_mov_b32_e32 v138, v159
	v_mov_b32_e32 v137, v159
	v_mov_b32_e32 v136, v159
	v_mov_b32_e32 v127, v159
	v_mov_b32_e32 v126, v159
	v_mov_b32_e32 v125, v159
	v_mov_b32_e32 v124, v159
	v_mov_b32_e32 v123, v159
	v_mov_b32_e32 v122, v159
	v_mov_b32_e32 v121, v159
	v_mov_b32_e32 v120, v159
	v_mov_b32_e32 v79, v159
	v_mov_b32_e32 v78, v159
	v_mov_b32_e32 v77, v159
	v_mov_b32_e32 v76, v159
	v_mov_b32_e32 v75, v159
	v_mov_b32_e32 v74, v159
	v_mov_b32_e32 v73, v159
	v_mov_b32_e32 v72, v159
	v_mov_b32_e32 v151, v159
	v_mov_b32_e32 v150, v159
	v_mov_b32_e32 v149, v159
	v_mov_b32_e32 v148, v159
	v_mov_b32_e32 v147, v159
	v_mov_b32_e32 v146, v159
	v_mov_b32_e32 v145, v159
	v_mov_b32_e32 v144, v159
	v_mov_b32_e32 v135, v159
	v_mov_b32_e32 v134, v159
	v_mov_b32_e32 v133, v159
	v_mov_b32_e32 v132, v159
	v_mov_b32_e32 v131, v159
	v_mov_b32_e32 v130, v159
	v_mov_b32_e32 v129, v159
	v_mov_b32_e32 v128, v159
	v_mov_b32_e32 v119, v159
	v_mov_b32_e32 v118, v159
	v_mov_b32_e32 v117, v159
	v_mov_b32_e32 v116, v159
	v_mov_b32_e32 v115, v159
	v_mov_b32_e32 v114, v159
	v_mov_b32_e32 v113, v159
	v_mov_b32_e32 v112, v159
	v_mov_b32_e32 v71, v159
	v_mov_b32_e32 v70, v159
	v_mov_b32_e32 v69, v159
	v_mov_b32_e32 v68, v159
	v_mov_b32_e32 v67, v159
	v_mov_b32_e32 v66, v159
	v_mov_b32_e32 v65, v159
	v_mov_b32_e32 v64, v159
	v_mov_b32_e32 v63, v159
	v_mov_b32_e32 v62, v159
	v_mov_b32_e32 v61, v159
	v_mov_b32_e32 v60, v159
	v_mov_b32_e32 v59, v159
	v_mov_b32_e32 v58, v159
	v_mov_b32_e32 v57, v159
	v_mov_b32_e32 v56, v159
	v_mov_b32_e32 v47, v159
	v_mov_b32_e32 v46, v159
	v_mov_b32_e32 v45, v159
	v_mov_b32_e32 v44, v159
	v_mov_b32_e32 v43, v159
	v_mov_b32_e32 v42, v159
	v_mov_b32_e32 v41, v159
	v_mov_b32_e32 v40, v159
	v_mov_b32_e32 v31, v159
	v_mov_b32_e32 v30, v159
	v_mov_b32_e32 v29, v159
	v_mov_b32_e32 v28, v159
	v_mov_b32_e32 v27, v159
	v_mov_b32_e32 v26, v159
	v_mov_b32_e32 v25, v159
	v_mov_b32_e32 v24, v159
	v_mov_b32_e32 v15, v159
	v_mov_b32_e32 v14, v159
	v_mov_b32_e32 v13, v159
	v_mov_b32_e32 v12, v159
	v_mov_b32_e32 v11, v159
	v_mov_b32_e32 v10, v159
	v_mov_b32_e32 v9, v159
	v_mov_b32_e32 v8, v159
	v_mov_b32_e32 v55, v159
	v_mov_b32_e32 v54, v159
	v_mov_b32_e32 v53, v159
	v_mov_b32_e32 v52, v159
	v_mov_b32_e32 v51, v159
	v_mov_b32_e32 v50, v159
	v_mov_b32_e32 v49, v159
	v_mov_b32_e32 v48, v159
	v_mov_b32_e32 v39, v159
	v_mov_b32_e32 v38, v159
	v_mov_b32_e32 v37, v159
	v_mov_b32_e32 v36, v159
	v_mov_b32_e32 v35, v159
	v_mov_b32_e32 v34, v159
	v_mov_b32_e32 v33, v159
	v_mov_b32_e32 v32, v159
	v_mov_b32_e32 v23, v159
	v_mov_b32_e32 v22, v159
	v_mov_b32_e32 v21, v159
	v_mov_b32_e32 v20, v159
	v_mov_b32_e32 v19, v159
	v_mov_b32_e32 v18, v159
	v_mov_b32_e32 v17, v159
	v_mov_b32_e32 v16, v159
	v_mov_b32_e32 v7, v159
	v_mov_b32_e32 v6, v159
	v_mov_b32_e32 v5, v159
	v_mov_b32_e32 v4, v159
	v_mov_b32_e32 v3, v159
	v_mov_b32_e32 v2, v159
	v_mov_b32_e32 v1, v159
	v_mov_b32_e32 v0, v159
	s_cbranch_vccnz .LBB0_854
	s_and_b64 s[26:27], s[38:39], exec
	s_cselect_b32 s1, s57, s21
	s_cselect_b32 s40, s56, s20
	s_cselect_b32 s41, s59, s23
	s_cselect_b32 s53, s58, s22
	s_add_u32 s20, s20, 0x40080
	s_addc_u32 s21, s21, 0
	s_add_u32 s55, s22, 0x100
	s_addc_u32 s71, s23, 0
	s_mov_b32 s22, 0

.LBB0_914:
	s_ashr_i32 s47, s46, 31
	s_lshl_b64 s[50:51], s[46:47], 19
	s_add_u32 s50, s34, s50
	s_addc_u32 s51, s60, s51
	v_mov_b32_e32 v127, 0
	s_andn2_b64 vcc, exec, s[20:21]
	v_mov_b32_e32 v126, 0
	v_mov_b32_e32 v125, 0
	v_mov_b32_e32 v124, 0
	v_mov_b32_e32 v123, 0
	v_mov_b32_e32 v122, 0
	v_mov_b32_e32 v121, 0
	v_mov_b32_e32 v120, 0
	v_mov_b32_e32 v111, 0
	v_mov_b32_e32 v110, 0
	v_mov_b32_e32 v109, 0
	v_mov_b32_e32 v108, 0
	v_mov_b32_e32 v107, 0
	v_mov_b32_e32 v106, 0
	v_mov_b32_e32 v105, 0
	v_mov_b32_e32 v104, 0
	v_mov_b32_e32 v95, 0
	v_mov_b32_e32 v94, 0
	v_mov_b32_e32 v93, 0
	v_mov_b32_e32 v92, 0
	v_mov_b32_e32 v91, 0
	v_mov_b32_e32 v90, 0
	v_mov_b32_e32 v89, 0
	v_mov_b32_e32 v88, 0
	v_mov_b32_e32 v79, 0
	v_mov_b32_e32 v78, 0
	v_mov_b32_e32 v77, 0
	v_mov_b32_e32 v76, 0
	v_mov_b32_e32 v75, 0
	v_mov_b32_e32 v74, 0
	v_mov_b32_e32 v73, 0
	v_mov_b32_e32 v72, 0
	v_mov_b32_e32 v119, 0
	v_mov_b32_e32 v118, 0
	v_mov_b32_e32 v117, 0
	v_mov_b32_e32 v116, 0
	v_mov_b32_e32 v115, 0
	v_mov_b32_e32 v114, 0
	v_mov_b32_e32 v113, 0
	v_mov_b32_e32 v112, 0
	v_mov_b32_e32 v103, 0
	v_mov_b32_e32 v102, 0
	v_mov_b32_e32 v101, 0
	v_mov_b32_e32 v100, 0
	v_mov_b32_e32 v99, 0
	v_mov_b32_e32 v98, 0
	v_mov_b32_e32 v97, 0
	v_mov_b32_e32 v96, 0
	v_mov_b32_e32 v87, 0
	v_mov_b32_e32 v86, 0
	v_mov_b32_e32 v85, 0
	v_mov_b32_e32 v84, 0
	v_mov_b32_e32 v83, 0
	v_mov_b32_e32 v82, 0
	v_mov_b32_e32 v81, 0
	v_mov_b32_e32 v80, 0
	v_mov_b32_e32 v71, 0
	v_mov_b32_e32 v70, 0
	v_mov_b32_e32 v69, 0
	v_mov_b32_e32 v68, 0
	v_mov_b32_e32 v67, 0
	v_mov_b32_e32 v66, 0
	v_mov_b32_e32 v65, 0
	v_mov_b32_e32 v64, 0
	v_mov_b32_e32 v63, 0
	v_mov_b32_e32 v62, 0
	v_mov_b32_e32 v61, 0
	v_mov_b32_e32 v60, 0
	v_mov_b32_e32 v59, 0
	v_mov_b32_e32 v58, 0
	v_mov_b32_e32 v57, 0
	v_mov_b32_e32 v56, 0
	v_mov_b32_e32 v47, 0
	v_mov_b32_e32 v46, 0
	v_mov_b32_e32 v45, 0
	v_mov_b32_e32 v44, 0
	v_mov_b32_e32 v43, 0
	v_mov_b32_e32 v42, 0
	v_mov_b32_e32 v41, 0
	v_mov_b32_e32 v40, 0
	v_mov_b32_e32 v31, 0
	v_mov_b32_e32 v30, 0
	v_mov_b32_e32 v29, 0
	v_mov_b32_e32 v28, 0
	v_mov_b32_e32 v27, 0
	v_mov_b32_e32 v26, 0
	v_mov_b32_e32 v25, 0
	v_mov_b32_e32 v24, 0
	v_mov_b32_e32 v15, 0
	v_mov_b32_e32 v14, 0
	v_mov_b32_e32 v13, 0
	v_mov_b32_e32 v12, 0
	v_mov_b32_e32 v11, 0
	v_mov_b32_e32 v10, 0
	v_mov_b32_e32 v9, 0
	v_mov_b32_e32 v8, 0
	v_mov_b32_e32 v55, 0
	v_mov_b32_e32 v54, 0
	v_mov_b32_e32 v53, 0
	v_mov_b32_e32 v52, 0
	v_mov_b32_e32 v51, 0
	v_mov_b32_e32 v50, 0
	v_mov_b32_e32 v49, 0
	v_mov_b32_e32 v48, 0
	v_mov_b32_e32 v39, 0
	v_mov_b32_e32 v38, 0
	v_mov_b32_e32 v37, 0
	v_mov_b32_e32 v36, 0
	v_mov_b32_e32 v35, 0
	v_mov_b32_e32 v34, 0
	v_mov_b32_e32 v33, 0
	v_mov_b32_e32 v32, 0
	v_mov_b32_e32 v23, 0
	v_mov_b32_e32 v22, 0
	v_mov_b32_e32 v21, 0
	v_mov_b32_e32 v20, 0
	v_mov_b32_e32 v19, 0
	v_mov_b32_e32 v18, 0
	v_mov_b32_e32 v17, 0
	v_mov_b32_e32 v16, 0
	v_mov_b32_e32 v7, 0
	v_mov_b32_e32 v6, 0
	v_mov_b32_e32 v5, 0
	v_mov_b32_e32 v4, 0
	v_mov_b32_e32 v3, 0
	v_mov_b32_e32 v2, 0
	v_mov_b32_e32 v1, 0
	v_mov_b32_e32 v0, 0
	s_cbranch_vccnz .LBB0_918
	s_and_b64 s[58:59], s[58:59], exec
	s_cselect_b32 s1, s51, s55
	s_cselect_b32 s3, s50, s54
	s_add_u32 s54, s54, 0x40080
	s_addc_u32 s55, s55, 0
	s_add_u32 s43, s56, 0x100
	s_addc_u32 s45, s57, 0
	s_mov_b32 s47, 0

.LBB0_978:
	v_mov_b32_e32 v127, 0
	s_andn2_b64 vcc, exec, s[20:21]
	v_mov_b32_e32 v126, 0
	v_mov_b32_e32 v125, 0
	v_mov_b32_e32 v124, 0
	v_mov_b32_e32 v123, 0
	v_mov_b32_e32 v122, 0
	v_mov_b32_e32 v121, 0
	v_mov_b32_e32 v120, 0
	v_mov_b32_e32 v111, 0
	v_mov_b32_e32 v110, 0
	v_mov_b32_e32 v109, 0
	v_mov_b32_e32 v108, 0
	v_mov_b32_e32 v107, 0
	v_mov_b32_e32 v106, 0
	v_mov_b32_e32 v105, 0
	v_mov_b32_e32 v104, 0
	v_mov_b32_e32 v95, 0
	v_mov_b32_e32 v94, 0
	v_mov_b32_e32 v93, 0
	v_mov_b32_e32 v92, 0
	v_mov_b32_e32 v91, 0
	v_mov_b32_e32 v90, 0
	v_mov_b32_e32 v89, 0
	v_mov_b32_e32 v88, 0
	v_mov_b32_e32 v79, 0
	v_mov_b32_e32 v78, 0
	v_mov_b32_e32 v77, 0
	v_mov_b32_e32 v76, 0
	v_mov_b32_e32 v75, 0
	v_mov_b32_e32 v74, 0
	v_mov_b32_e32 v73, 0
	v_mov_b32_e32 v72, 0
	v_mov_b32_e32 v119, 0
	v_mov_b32_e32 v118, 0
	v_mov_b32_e32 v117, 0
	v_mov_b32_e32 v116, 0
	v_mov_b32_e32 v115, 0
	v_mov_b32_e32 v114, 0
	v_mov_b32_e32 v113, 0
	v_mov_b32_e32 v112, 0
	v_mov_b32_e32 v103, 0
	v_mov_b32_e32 v102, 0
	v_mov_b32_e32 v101, 0
	v_mov_b32_e32 v100, 0
	v_mov_b32_e32 v99, 0
	v_mov_b32_e32 v98, 0
	v_mov_b32_e32 v97, 0
	v_mov_b32_e32 v96, 0
	v_mov_b32_e32 v87, 0
	v_mov_b32_e32 v86, 0
	v_mov_b32_e32 v85, 0
	v_mov_b32_e32 v84, 0
	v_mov_b32_e32 v83, 0
	v_mov_b32_e32 v82, 0
	v_mov_b32_e32 v81, 0
	v_mov_b32_e32 v80, 0
	v_mov_b32_e32 v71, 0
	v_mov_b32_e32 v70, 0
	v_mov_b32_e32 v69, 0
	v_mov_b32_e32 v68, 0
	v_mov_b32_e32 v67, 0
	v_mov_b32_e32 v66, 0
	v_mov_b32_e32 v65, 0
	v_mov_b32_e32 v64, 0
	v_mov_b32_e32 v63, 0
	v_mov_b32_e32 v62, 0
	v_mov_b32_e32 v61, 0
	v_mov_b32_e32 v60, 0
	v_mov_b32_e32 v59, 0
	v_mov_b32_e32 v58, 0
	v_mov_b32_e32 v57, 0
	v_mov_b32_e32 v56, 0
	v_mov_b32_e32 v47, 0
	v_mov_b32_e32 v46, 0
	v_mov_b32_e32 v45, 0
	v_mov_b32_e32 v44, 0
	v_mov_b32_e32 v43, 0
	v_mov_b32_e32 v42, 0
	v_mov_b32_e32 v41, 0
	v_mov_b32_e32 v40, 0
	v_mov_b32_e32 v31, 0
	v_mov_b32_e32 v30, 0
	v_mov_b32_e32 v29, 0
	v_mov_b32_e32 v28, 0
	v_mov_b32_e32 v27, 0
	v_mov_b32_e32 v26, 0
	v_mov_b32_e32 v25, 0
	v_mov_b32_e32 v24, 0
	v_mov_b32_e32 v15, 0
	v_mov_b32_e32 v14, 0
	v_mov_b32_e32 v13, 0
	v_mov_b32_e32 v12, 0
	v_mov_b32_e32 v11, 0
	v_mov_b32_e32 v10, 0
	v_mov_b32_e32 v9, 0
	v_mov_b32_e32 v8, 0
	v_mov_b32_e32 v55, 0
	v_mov_b32_e32 v54, 0
	v_mov_b32_e32 v53, 0
	v_mov_b32_e32 v52, 0
	v_mov_b32_e32 v51, 0
	v_mov_b32_e32 v50, 0
	v_mov_b32_e32 v49, 0
	v_mov_b32_e32 v48, 0
	v_mov_b32_e32 v39, 0
	v_mov_b32_e32 v38, 0
	v_mov_b32_e32 v37, 0
	v_mov_b32_e32 v36, 0
	v_mov_b32_e32 v35, 0
	v_mov_b32_e32 v34, 0
	v_mov_b32_e32 v33, 0
	v_mov_b32_e32 v32, 0
	v_mov_b32_e32 v23, 0
	v_mov_b32_e32 v22, 0
	v_mov_b32_e32 v21, 0
	v_mov_b32_e32 v20, 0
	v_mov_b32_e32 v19, 0
	v_mov_b32_e32 v18, 0
	v_mov_b32_e32 v17, 0
	v_mov_b32_e32 v16, 0
	v_mov_b32_e32 v7, 0
	v_mov_b32_e32 v6, 0
	v_mov_b32_e32 v5, 0
	v_mov_b32_e32 v4, 0
	v_mov_b32_e32 v3, 0
	v_mov_b32_e32 v2, 0
	v_mov_b32_e32 v1, 0
	v_mov_b32_e32 v0, 0
	s_cbranch_vccnz .LBB0_982
	s_add_u32 s50, s50, 0x40080
	s_addc_u32 s51, s51, 0
	s_add_u32 s1, s52, 0x100
	s_addc_u32 s3, s53, 0
	s_mov_b32 s41, 0

.LBB0_1030:
	s_ashr_i32 s41, s40, 31
	s_lshl_b64 s[2:3], s[40:41], 19
	v_readlane_b32 s44, v254, 43
	v_readlane_b32 s45, v254, 44
	s_add_u32 s2, s44, s2
	s_addc_u32 s3, s45, s3
	s_ashr_i32 s43, s42, 31
	s_lshl_b64 s[44:45], s[42:43], 19
	v_readlane_b32 s1, v254, 41
	s_add_u32 s44, s1, s44
	v_readlane_b32 s1, v254, 42
	s_addc_u32 s45, s1, s45
	v_mov_b32_e32 v127, 0
	s_andn2_b64 vcc, exec, s[22:23]
	v_mov_b32_e32 v126, 0
	v_mov_b32_e32 v125, 0
	v_mov_b32_e32 v124, 0
	v_mov_b32_e32 v123, 0
	v_mov_b32_e32 v122, 0
	v_mov_b32_e32 v121, 0
	v_mov_b32_e32 v120, 0
	v_mov_b32_e32 v111, 0
	v_mov_b32_e32 v110, 0
	v_mov_b32_e32 v109, 0
	v_mov_b32_e32 v108, 0
	v_mov_b32_e32 v107, 0
	v_mov_b32_e32 v106, 0
	v_mov_b32_e32 v105, 0
	v_mov_b32_e32 v104, 0
	v_mov_b32_e32 v95, 0
	v_mov_b32_e32 v94, 0
	v_mov_b32_e32 v93, 0
	v_mov_b32_e32 v92, 0
	v_mov_b32_e32 v91, 0
	v_mov_b32_e32 v90, 0
	v_mov_b32_e32 v89, 0
	v_mov_b32_e32 v88, 0
	v_mov_b32_e32 v79, 0
	v_mov_b32_e32 v78, 0
	v_mov_b32_e32 v77, 0
	v_mov_b32_e32 v76, 0
	v_mov_b32_e32 v75, 0
	v_mov_b32_e32 v74, 0
	v_mov_b32_e32 v73, 0
	v_mov_b32_e32 v72, 0
	v_mov_b32_e32 v119, 0
	v_mov_b32_e32 v118, 0
	v_mov_b32_e32 v117, 0
	v_mov_b32_e32 v116, 0
	v_mov_b32_e32 v115, 0
	v_mov_b32_e32 v114, 0
	v_mov_b32_e32 v113, 0
	v_mov_b32_e32 v112, 0
	v_mov_b32_e32 v103, 0
	v_mov_b32_e32 v102, 0
	v_mov_b32_e32 v101, 0
	v_mov_b32_e32 v100, 0
	v_mov_b32_e32 v99, 0
	v_mov_b32_e32 v98, 0
	v_mov_b32_e32 v97, 0
	v_mov_b32_e32 v96, 0
	v_mov_b32_e32 v87, 0
	v_mov_b32_e32 v86, 0
	v_mov_b32_e32 v85, 0
	v_mov_b32_e32 v84, 0
	v_mov_b32_e32 v83, 0
	v_mov_b32_e32 v82, 0
	v_mov_b32_e32 v81, 0
	v_mov_b32_e32 v80, 0
	v_mov_b32_e32 v71, 0
	v_mov_b32_e32 v70, 0
	v_mov_b32_e32 v69, 0
	v_mov_b32_e32 v68, 0
	v_mov_b32_e32 v67, 0
	v_mov_b32_e32 v66, 0
	v_mov_b32_e32 v65, 0
	v_mov_b32_e32 v64, 0
	v_mov_b32_e32 v63, 0
	v_mov_b32_e32 v62, 0
	v_mov_b32_e32 v61, 0
	v_mov_b32_e32 v60, 0
	v_mov_b32_e32 v59, 0
	v_mov_b32_e32 v58, 0
	v_mov_b32_e32 v57, 0
	v_mov_b32_e32 v56, 0
	v_mov_b32_e32 v47, 0
	v_mov_b32_e32 v46, 0
	v_mov_b32_e32 v45, 0
	v_mov_b32_e32 v44, 0
	v_mov_b32_e32 v43, 0
	v_mov_b32_e32 v42, 0
	v_mov_b32_e32 v41, 0
	v_mov_b32_e32 v40, 0
	v_mov_b32_e32 v31, 0
	v_mov_b32_e32 v30, 0
	v_mov_b32_e32 v29, 0
	v_mov_b32_e32 v28, 0
	v_mov_b32_e32 v27, 0
	v_mov_b32_e32 v26, 0
	v_mov_b32_e32 v25, 0
	v_mov_b32_e32 v24, 0
	v_mov_b32_e32 v15, 0
	v_mov_b32_e32 v14, 0
	v_mov_b32_e32 v13, 0
	v_mov_b32_e32 v12, 0
	v_mov_b32_e32 v11, 0
	v_mov_b32_e32 v10, 0
	v_mov_b32_e32 v9, 0
	v_mov_b32_e32 v8, 0
	v_mov_b32_e32 v55, 0
	v_mov_b32_e32 v54, 0
	v_mov_b32_e32 v53, 0
	v_mov_b32_e32 v52, 0
	v_mov_b32_e32 v51, 0
	v_mov_b32_e32 v50, 0
	v_mov_b32_e32 v49, 0
	v_mov_b32_e32 v48, 0
	v_mov_b32_e32 v39, 0
	v_mov_b32_e32 v38, 0
	v_mov_b32_e32 v37, 0
	v_mov_b32_e32 v36, 0
	v_mov_b32_e32 v35, 0
	v_mov_b32_e32 v34, 0
	v_mov_b32_e32 v33, 0
	v_mov_b32_e32 v32, 0
	v_mov_b32_e32 v23, 0
	v_mov_b32_e32 v22, 0
	v_mov_b32_e32 v21, 0
	v_mov_b32_e32 v20, 0
	v_mov_b32_e32 v19, 0
	v_mov_b32_e32 v18, 0
	v_mov_b32_e32 v17, 0
	v_mov_b32_e32 v16, 0
	v_mov_b32_e32 v7, 0
	v_mov_b32_e32 v6, 0
	v_mov_b32_e32 v5, 0
	v_mov_b32_e32 v4, 0
	v_mov_b32_e32 v3, 0
	v_mov_b32_e32 v2, 0
	v_mov_b32_e32 v1, 0
	v_mov_b32_e32 v0, 0
	s_cbranch_vccnz .LBB0_1033
	s_and_b64 s[52:53], s[38:39], exec
	s_cselect_b32 s1, s3, s49
	s_cselect_b32 s41, s2, s48
	s_cselect_b32 s43, s45, s51
	s_cselect_b32 s47, s44, s50
	s_add_u32 s48, s48, 0x40080
	s_addc_u32 s49, s49, 0
	s_add_u32 s67, s50, 0x100
	s_addc_u32 s68, s51, 0
	s_mov_b32 s50, 0
